# v109 + phase 2 epilogue halves straight-line: all row sums and rope rows of 4 steps requested up front, rope registers refilled after use (was 2 dependent L2 round trips per row)
# speedup vs baseline: 1.0112x; 1.0013x over previous
.LBB0_358:
	s_or_b64 exec, exec, s[6:7]
	s_waitcnt vmcnt(0)
	s_barrier
	ds_write2_b32 v219, v120, v124 offset1:16
	v_add_u32_e32 v120, 0x400, v219
	ds_write2_b32 v120, v121, v125 offset0:4 offset1:20
	v_add_u32_e32 v121, 0x800, v219
	ds_write2_b32 v121, v122, v126 offset0:8 offset1:24
	v_add_u32_e32 v122, 0xc00, v219
	ds_write2_b32 v122, v123, v127 offset0:12 offset1:28
	v_add_u32_e32 v123, 0x4000, v219
	ds_write2_b32 v123, v80, v92 offset0:64 offset1:80
	v_add_u32_e32 v80, 0x4400, v219
	ds_write2_b32 v80, v81, v93 offset0:68 offset1:84
	v_add_u32_e32 v81, 0x4800, v219
	ds_write2_b32 v81, v82, v94 offset0:72 offset1:88
	v_add_u32_e32 v82, 0x4c00, v219
	ds_write2_b32 v82, v83, v95 offset0:76 offset1:92
	v_add_u32_e32 v83, 0x8000, v219
	ds_write2_b32 v83, v72, v76 offset0:128 offset1:144
	v_add_u32_e32 v72, 0x8400, v219
	ds_write2_b32 v72, v73, v77 offset0:132 offset1:148
	v_add_u32_e32 v73, 0x8800, v219
	ds_write2_b32 v73, v74, v78 offset0:136 offset1:152
	v_add_u32_e32 v74, 0x8c00, v219
	ds_write2_b32 v74, v75, v79 offset0:140 offset1:156
	v_add_u32_e32 v75, 0xc000, v219
	v_lshlrev_b32_e32 v128, 1, v210
	v_and_b32_e32 v133, 15, v210
	ds_write2_b32 v75, v64, v68 offset0:192 offset1:208
	v_add_u32_e32 v64, 0xc400, v219
	v_and_b32_e32 v216, 0x80, v128
	v_lshlrev_b32_e32 v128, 4, v133
	v_mov_b32_e32 v129, 0
	ds_write2_b32 v64, v65, v69 offset0:196 offset1:212
	v_add_u32_e32 v65, 0xc800, v219
	v_lshl_add_u64 v[130:131], s[38:39], 0, v[128:129]
	v_lshlrev_b32_e32 v128, 5, v210
	ds_write2_b32 v65, v66, v70 offset0:200 offset1:216
	v_add_u32_e32 v66, 0xcc00, v219
	v_ashrrev_i32_e32 v132, 2, v210
	s_mov_b64 s[6:7], 0x2080000
	v_and_b32_e32 v128, 32, v128
	ds_write2_b32 v66, v67, v71 offset0:204 offset1:220
	ds_write2_b32 v219, v96, v112 offset0:128 offset1:144
	ds_write2_b32 v120, v97, v113 offset0:132 offset1:148
	ds_write2_b32 v121, v98, v114 offset0:136 offset1:152
	ds_write2_b32 v122, v99, v115 offset0:140 offset1:156
	ds_write2_b32 v123, v100, v116 offset0:192 offset1:208
	ds_write2_b32 v80, v101, v117 offset0:196 offset1:212
	ds_write2_b32 v81, v102, v118 offset0:200 offset1:216
	ds_write2_b32 v82, v103, v119 offset0:204 offset1:220
	ds_write2_b32 v72, v88, v108 offset1:16
	ds_write2_b32 v73, v89, v109 offset0:4 offset1:20
	ds_write2_b32 v74, v90, v110 offset0:8 offset1:24
	v_add_u32_e32 v67, 0x9000, v219
	s_add_u32 s12, s38, 0xe9b8400
	v_bfe_u32 v211, v210, 4, 2
	v_lshl_add_u64 v[196:197], v[130:131], 0, s[6:7]
	v_lshl_add_u64 v[130:131], s[38:39], 0, v[128:129]
	v_or_b32_e32 v128, s62, v216
	ds_write2_b32 v67, v91, v111 offset0:12 offset1:28
	ds_write2_b32 v64, v84, v104 offset0:64 offset1:80
	ds_write2_b32 v65, v85, v105 offset0:68 offset1:84
	ds_write2_b32 v66, v86, v106 offset0:72 offset1:88
	v_add_u32_e32 v64, 0xd000, v219
	v_lshrrev_b32_e32 v66, 5, v132
	s_mov_b32 s8, 0x8200
	v_lshlrev_b32_e32 v68, 3, v210
	s_addc_u32 s13, s39, 0
	v_bfe_u32 v215, v210, 2, 2
	ds_write2_b32 v64, v87, v107 offset0:76 offset1:92
	v_lshrrev_b32_e32 v64, 5, v128
	v_mul_lo_u32 v66, v66, s8
	v_mul_u32_u24_e32 v67, 0x410, v211
	v_and_b32_e32 v68, 0x200, v68
	s_bfe_u32 s66, s86, 0x30005
	v_and_b32_e32 v134, 2, v210
	v_or_b32_e32 v64, v64, v215
	v_add3_u32 v66, v66, v67, v68
	v_lshlrev_b32_e32 v67, 5, v133
	s_lshl_b32 s64, s66, 11
	v_cmp_eq_u32_e32 vcc, 0, v134
	v_mul_lo_u16_e32 v64, 0xffcd, v64
	v_add3_u32 v212, v66, v67, 0
	v_or_b32_e32 v66, s64, v211
	s_lshl_b32 s65, s85, 8
	v_and_b32_e32 v213, 0xffffffe0, v132
	s_mov_b64 s[6:7], 0xe9d8c00
	v_cndmask_b32_e64 v194, 1.0, -1.0, vcc
	v_subrev_u16_e32 v64, 52, v64
	v_mov_b32_e32 v65, 51
	v_lshlrev_b32_e32 v128, 1, v128
	v_or_b32_e32 v66, s65, v66
	v_lshl_add_u64 v[192:193], v[130:131], 0, s[6:7]
	s_mov_b32 s10, 0
	s_movk_i32 s11, 0x4000
	v_cmp_lt_u16_sdwa s[6:7], v64, v65 src0_sel:BYTE_0 src1_sel:DWORD
	v_lshl_add_u64 v[64:65], v[196:197], 0, v[128:129]
	v_mov_b32_e32 v195, v194
	v_add_u32_e32 v82, v66, v213
	v_mov_b32_e32 v83, 0x358637bd
	s_mov_b32 s14, 0x800000
	s_movk_i32 s15, 0xa00
	v_mov_b32_e32 v84, 0x400
	v_mov_b32_e32 v85, v212
	s_waitcnt lgkmcnt(0)
	s_barrier
	v_mov_b32_e32 v198, v82
	v_add_u32_e32 v244, 0, v198
	v_ashrrev_i32_e32 v245, 31, v244
	v_lshl_add_u64 v[244:245], v[244:245], 2, s[12:13]
	global_load_dword v220, v[244:245], off
	v_add_u32_e32 v244, 4, v198
	v_ashrrev_i32_e32 v245, 31, v244
	v_lshl_add_u64 v[244:245], v[244:245], 2, s[12:13]
	global_load_dword v221, v[244:245], off
	v_add_u32_e32 v244, 8, v198
	v_ashrrev_i32_e32 v245, 31, v244
	v_lshl_add_u64 v[244:245], v[244:245], 2, s[12:13]
	global_load_dword v222, v[244:245], off
	v_add_u32_e32 v244, 12, v198
	v_ashrrev_i32_e32 v245, 31, v244
	v_lshl_add_u64 v[244:245], v[244:245], 2, s[12:13]
	global_load_dword v223, v[244:245], off
	v_add_u32_e32 v244, 16, v198
	v_ashrrev_i32_e32 v245, 31, v244
	v_lshl_add_u64 v[244:245], v[244:245], 2, s[12:13]
	global_load_dword v224, v[244:245], off
	v_add_u32_e32 v244, 20, v198
	v_ashrrev_i32_e32 v245, 31, v244
	v_lshl_add_u64 v[244:245], v[244:245], 2, s[12:13]
	global_load_dword v225, v[244:245], off
	v_add_u32_e32 v244, 24, v198
	v_ashrrev_i32_e32 v245, 31, v244
	v_lshl_add_u64 v[244:245], v[244:245], 2, s[12:13]
	global_load_dword v226, v[244:245], off
	v_add_u32_e32 v244, 28, v198
	v_ashrrev_i32_e32 v245, 31, v244
	v_lshl_add_u64 v[244:245], v[244:245], 2, s[12:13]
	global_load_dword v227, v[244:245], off
	v_add_u32_e32 v244, 0, v198
	v_and_b32_e32 v245, 0x1fff, v244
	v_add_u32_e32 v246, 0, v211
	v_and_or_b32 v246, v246, 15, v84
	v_cmp_gt_i32_e32 vcc, s11, v244
	s_nop 1
	v_cndmask_b32_e32 v245, v246, v245, vcc
	v_lshlrev_b32_e32 v246, 7, v245
	v_mov_b32_e32 v247, 0
	v_lshl_add_u64 v[246:247], v[192:193], 0, v[246:247]
	global_load_dwordx4 v[130:133], v[246:247], off offset:64
	global_load_dwordx4 v[134:137], v[246:247], off offset:80
	global_load_dwordx4 v[138:141], v[246:247], off offset:16
	global_load_dwordx4 v[142:145], v[246:247], off
	v_add_u32_e32 v244, 4, v198
	v_and_b32_e32 v245, 0x1fff, v244
	v_add_u32_e32 v246, 4, v211
	v_and_or_b32 v246, v246, 15, v84
	v_cmp_gt_i32_e32 vcc, s11, v244
	s_nop 1
	v_cndmask_b32_e32 v245, v246, v245, vcc
	v_lshlrev_b32_e32 v246, 7, v245
	v_mov_b32_e32 v247, 0
	v_lshl_add_u64 v[246:247], v[192:193], 0, v[246:247]
	global_load_dwordx4 v[146:149], v[246:247], off offset:64
	global_load_dwordx4 v[150:153], v[246:247], off offset:80
	global_load_dwordx4 v[154:157], v[246:247], off offset:16
	global_load_dwordx4 v[158:161], v[246:247], off
	v_add_u32_e32 v244, 8, v198
	v_and_b32_e32 v245, 0x1fff, v244
	v_add_u32_e32 v246, 8, v211
	v_and_or_b32 v246, v246, 15, v84
	v_cmp_gt_i32_e32 vcc, s11, v244
	s_nop 1
	v_cndmask_b32_e32 v245, v246, v245, vcc
	v_lshlrev_b32_e32 v246, 7, v245
	v_mov_b32_e32 v247, 0
	v_lshl_add_u64 v[246:247], v[192:193], 0, v[246:247]
	global_load_dwordx4 v[162:165], v[246:247], off offset:64
	global_load_dwordx4 v[166:169], v[246:247], off offset:80
	global_load_dwordx4 v[170:173], v[246:247], off offset:16
	global_load_dwordx4 v[174:177], v[246:247], off
	v_add_u32_e32 v244, 12, v198
	v_and_b32_e32 v245, 0x1fff, v244
	v_add_u32_e32 v246, 12, v211
	v_and_or_b32 v246, v246, 15, v84
	v_cmp_gt_i32_e32 vcc, s11, v244
	s_nop 1
	v_cndmask_b32_e32 v245, v246, v245, vcc
	v_lshlrev_b32_e32 v246, 7, v245
	v_mov_b32_e32 v247, 0
	v_lshl_add_u64 v[246:247], v[192:193], 0, v[246:247]
	global_load_dwordx4 v[88:91], v[246:247], off offset:64
	global_load_dwordx4 v[92:95], v[246:247], off offset:80
	global_load_dwordx4 v[96:99], v[246:247], off offset:16
	global_load_dwordx4 v[100:103], v[246:247], off
	ds_read_b128 v[104:107], v85 offset:0
	ds_read_b128 v[108:111], v85 offset:16
	v_add_u32_e32 v240, 0, v198
	v_mad_i64_i32 v[240:241], s[8:9], v240, s15, v[64:65]
	s_waitcnt vmcnt(12)
	v_fmamk_f32 v236, v220, 0x3b800000, v83
	v_mul_f32_e32 v237, 0x4b800000, v236
	v_cmp_gt_f32_e32 vcc, s14, v236
	s_nop 1
	v_cndmask_b32_e32 v236, v236, v237, vcc
	v_rsq_f32_e32 v236, v236
	s_nop 0
	v_mul_f32_e32 v237, 0x45800000, v236
	v_cndmask_b32_e32 v236, v236, v237, vcc
	s_waitcnt lgkmcnt(0)
	v_pk_mul_f32 v[104:105], v[104:105], v[236:237] op_sel_hi:[1,0]
	v_pk_mul_f32 v[106:107], v[106:107], v[236:237] op_sel_hi:[1,0]
	v_pk_mul_f32 v[108:109], v[108:109], v[236:237] op_sel_hi:[1,0]
	v_pk_mul_f32 v[110:111], v[110:111], v[236:237] op_sel_hi:[1,0]
	s_nop 1
	v_mov_b32_dpp v120, v104 quad_perm:[2,3,0,1] row_mask:0xf bank_mask:0xf bound_ctrl:1
	v_mov_b32_dpp v121, v105 quad_perm:[2,3,0,1] row_mask:0xf bank_mask:0xf bound_ctrl:1
	v_mov_b32_dpp v122, v106 quad_perm:[2,3,0,1] row_mask:0xf bank_mask:0xf bound_ctrl:1
	v_mov_b32_dpp v123, v107 quad_perm:[2,3,0,1] row_mask:0xf bank_mask:0xf bound_ctrl:1
	v_mov_b32_dpp v124, v108 quad_perm:[2,3,0,1] row_mask:0xf bank_mask:0xf bound_ctrl:1
	v_mov_b32_dpp v125, v109 quad_perm:[2,3,0,1] row_mask:0xf bank_mask:0xf bound_ctrl:1
	v_mov_b32_dpp v126, v110 quad_perm:[2,3,0,1] row_mask:0xf bank_mask:0xf bound_ctrl:1
	v_mov_b32_dpp v127, v111 quad_perm:[2,3,0,1] row_mask:0xf bank_mask:0xf bound_ctrl:1
	s_and_saveexec_b64 s[8:9], s[6:7]
	v_pk_mul_f32 v[120:121], v[194:195], v[120:121]
	v_pk_mul_f32 v[122:123], v[194:195], v[122:123]
	v_pk_mul_f32 v[124:125], v[194:195], v[124:125]
	v_pk_mul_f32 v[126:127], v[194:195], v[126:127]
	v_pk_mul_f32 v[120:121], v[120:121], v[130:131]
	v_pk_mul_f32 v[122:123], v[122:123], v[132:133]
	v_pk_mul_f32 v[124:125], v[124:125], v[134:135]
	v_pk_mul_f32 v[126:127], v[126:127], v[136:137]
	v_pk_fma_f32 v[104:105], v[104:105], v[142:143], v[120:121]
	v_pk_fma_f32 v[106:107], v[106:107], v[144:145], v[122:123]
	v_pk_fma_f32 v[108:109], v[108:109], v[138:139], v[124:125]
	v_pk_fma_f32 v[110:111], v[110:111], v[140:141], v[126:127]
	s_or_b64 exec, exec, s[8:9]
	v_cvt_pk_bf16_f32 v104, v104, v105
	v_cvt_pk_bf16_f32 v105, v106, v107
	v_cvt_pk_bf16_f32 v106, v108, v109
	v_cvt_pk_bf16_f32 v107, v110, v111
	global_store_dwordx4 v[240:241], v[104:107], off
	v_add_u32_e32 v244, 16, v198
	v_and_b32_e32 v245, 0x1fff, v244
	v_add_u32_e32 v246, 16, v211
	v_and_or_b32 v246, v246, 15, v84
	v_cmp_gt_i32_e32 vcc, s11, v244
	s_nop 1
	v_cndmask_b32_e32 v245, v246, v245, vcc
	v_lshlrev_b32_e32 v246, 7, v245
	v_mov_b32_e32 v247, 0
	v_lshl_add_u64 v[246:247], v[192:193], 0, v[246:247]
	global_load_dwordx4 v[130:133], v[246:247], off offset:64
	global_load_dwordx4 v[134:137], v[246:247], off offset:80
	global_load_dwordx4 v[138:141], v[246:247], off offset:16
	global_load_dwordx4 v[142:145], v[246:247], off
	ds_read_b128 v[112:115], v85 offset:4160
	ds_read_b128 v[116:119], v85 offset:4176
	v_add_u32_e32 v242, 4, v198
	v_mad_i64_i32 v[242:243], s[8:9], v242, s15, v[64:65]
	s_waitcnt vmcnt(13)
	v_fmamk_f32 v238, v221, 0x3b800000, v83
	v_mul_f32_e32 v239, 0x4b800000, v238
	v_cmp_gt_f32_e32 vcc, s14, v238
	s_nop 1
	v_cndmask_b32_e32 v238, v238, v239, vcc
	v_rsq_f32_e32 v238, v238
	s_nop 0
	v_mul_f32_e32 v239, 0x45800000, v238
	v_cndmask_b32_e32 v238, v238, v239, vcc
	s_waitcnt lgkmcnt(0)
	v_pk_mul_f32 v[112:113], v[112:113], v[238:239] op_sel_hi:[1,0]
	v_pk_mul_f32 v[114:115], v[114:115], v[238:239] op_sel_hi:[1,0]
	v_pk_mul_f32 v[116:117], v[116:117], v[238:239] op_sel_hi:[1,0]
	v_pk_mul_f32 v[118:119], v[118:119], v[238:239] op_sel_hi:[1,0]
	s_nop 1
	v_mov_b32_dpp v228, v112 quad_perm:[2,3,0,1] row_mask:0xf bank_mask:0xf bound_ctrl:1
	v_mov_b32_dpp v229, v113 quad_perm:[2,3,0,1] row_mask:0xf bank_mask:0xf bound_ctrl:1
	v_mov_b32_dpp v230, v114 quad_perm:[2,3,0,1] row_mask:0xf bank_mask:0xf bound_ctrl:1
	v_mov_b32_dpp v231, v115 quad_perm:[2,3,0,1] row_mask:0xf bank_mask:0xf bound_ctrl:1
	v_mov_b32_dpp v232, v116 quad_perm:[2,3,0,1] row_mask:0xf bank_mask:0xf bound_ctrl:1
	v_mov_b32_dpp v233, v117 quad_perm:[2,3,0,1] row_mask:0xf bank_mask:0xf bound_ctrl:1
	v_mov_b32_dpp v234, v118 quad_perm:[2,3,0,1] row_mask:0xf bank_mask:0xf bound_ctrl:1
	v_mov_b32_dpp v235, v119 quad_perm:[2,3,0,1] row_mask:0xf bank_mask:0xf bound_ctrl:1
	s_and_saveexec_b64 s[8:9], s[6:7]
	v_pk_mul_f32 v[228:229], v[194:195], v[228:229]
	v_pk_mul_f32 v[230:231], v[194:195], v[230:231]
	v_pk_mul_f32 v[232:233], v[194:195], v[232:233]
	v_pk_mul_f32 v[234:235], v[194:195], v[234:235]
	v_pk_mul_f32 v[228:229], v[228:229], v[146:147]
	v_pk_mul_f32 v[230:231], v[230:231], v[148:149]
	v_pk_mul_f32 v[232:233], v[232:233], v[150:151]
	v_pk_mul_f32 v[234:235], v[234:235], v[152:153]
	v_pk_fma_f32 v[112:113], v[112:113], v[158:159], v[228:229]
	v_pk_fma_f32 v[114:115], v[114:115], v[160:161], v[230:231]
	v_pk_fma_f32 v[116:117], v[116:117], v[154:155], v[232:233]
	v_pk_fma_f32 v[118:119], v[118:119], v[156:157], v[234:235]
	s_or_b64 exec, exec, s[8:9]
	v_cvt_pk_bf16_f32 v112, v112, v113
	v_cvt_pk_bf16_f32 v113, v114, v115
	v_cvt_pk_bf16_f32 v114, v116, v117
	v_cvt_pk_bf16_f32 v115, v118, v119
	global_store_dwordx4 v[242:243], v[112:115], off
	v_add_u32_e32 v244, 20, v198
	v_and_b32_e32 v245, 0x1fff, v244
	v_add_u32_e32 v246, 20, v211
	v_and_or_b32 v246, v246, 15, v84
	v_cmp_gt_i32_e32 vcc, s11, v244
	s_nop 1
	v_cndmask_b32_e32 v245, v246, v245, vcc
	v_lshlrev_b32_e32 v246, 7, v245
	v_mov_b32_e32 v247, 0
	v_lshl_add_u64 v[246:247], v[192:193], 0, v[246:247]
	global_load_dwordx4 v[146:149], v[246:247], off offset:64
	global_load_dwordx4 v[150:153], v[246:247], off offset:80
	global_load_dwordx4 v[154:157], v[246:247], off offset:16
	global_load_dwordx4 v[158:161], v[246:247], off
	ds_read_b128 v[104:107], v85 offset:8320
	ds_read_b128 v[108:111], v85 offset:8336
	v_add_u32_e32 v240, 8, v198
	v_mad_i64_i32 v[240:241], s[8:9], v240, s15, v[64:65]
	s_waitcnt vmcnt(14)
	v_fmamk_f32 v236, v222, 0x3b800000, v83
	v_mul_f32_e32 v237, 0x4b800000, v236
	v_cmp_gt_f32_e32 vcc, s14, v236
	s_nop 1
	v_cndmask_b32_e32 v236, v236, v237, vcc
	v_rsq_f32_e32 v236, v236
	s_nop 0
	v_mul_f32_e32 v237, 0x45800000, v236
	v_cndmask_b32_e32 v236, v236, v237, vcc
	s_waitcnt lgkmcnt(0)
	v_pk_mul_f32 v[104:105], v[104:105], v[236:237] op_sel_hi:[1,0]
	v_pk_mul_f32 v[106:107], v[106:107], v[236:237] op_sel_hi:[1,0]
	v_pk_mul_f32 v[108:109], v[108:109], v[236:237] op_sel_hi:[1,0]
	v_pk_mul_f32 v[110:111], v[110:111], v[236:237] op_sel_hi:[1,0]
	s_nop 1
	v_mov_b32_dpp v120, v104 quad_perm:[2,3,0,1] row_mask:0xf bank_mask:0xf bound_ctrl:1
	v_mov_b32_dpp v121, v105 quad_perm:[2,3,0,1] row_mask:0xf bank_mask:0xf bound_ctrl:1
	v_mov_b32_dpp v122, v106 quad_perm:[2,3,0,1] row_mask:0xf bank_mask:0xf bound_ctrl:1
	v_mov_b32_dpp v123, v107 quad_perm:[2,3,0,1] row_mask:0xf bank_mask:0xf bound_ctrl:1
	v_mov_b32_dpp v124, v108 quad_perm:[2,3,0,1] row_mask:0xf bank_mask:0xf bound_ctrl:1
	v_mov_b32_dpp v125, v109 quad_perm:[2,3,0,1] row_mask:0xf bank_mask:0xf bound_ctrl:1
	v_mov_b32_dpp v126, v110 quad_perm:[2,3,0,1] row_mask:0xf bank_mask:0xf bound_ctrl:1
	v_mov_b32_dpp v127, v111 quad_perm:[2,3,0,1] row_mask:0xf bank_mask:0xf bound_ctrl:1
	s_and_saveexec_b64 s[8:9], s[6:7]
	v_pk_mul_f32 v[120:121], v[194:195], v[120:121]
	v_pk_mul_f32 v[122:123], v[194:195], v[122:123]
	v_pk_mul_f32 v[124:125], v[194:195], v[124:125]
	v_pk_mul_f32 v[126:127], v[194:195], v[126:127]
	v_pk_mul_f32 v[120:121], v[120:121], v[162:163]
	v_pk_mul_f32 v[122:123], v[122:123], v[164:165]
	v_pk_mul_f32 v[124:125], v[124:125], v[166:167]
	v_pk_mul_f32 v[126:127], v[126:127], v[168:169]
	v_pk_fma_f32 v[104:105], v[104:105], v[174:175], v[120:121]
	v_pk_fma_f32 v[106:107], v[106:107], v[176:177], v[122:123]
	v_pk_fma_f32 v[108:109], v[108:109], v[170:171], v[124:125]
	v_pk_fma_f32 v[110:111], v[110:111], v[172:173], v[126:127]
	s_or_b64 exec, exec, s[8:9]
	v_cvt_pk_bf16_f32 v104, v104, v105
	v_cvt_pk_bf16_f32 v105, v106, v107
	v_cvt_pk_bf16_f32 v106, v108, v109
	v_cvt_pk_bf16_f32 v107, v110, v111
	global_store_dwordx4 v[240:241], v[104:107], off
	v_add_u32_e32 v244, 24, v198
	v_and_b32_e32 v245, 0x1fff, v244
	v_add_u32_e32 v246, 24, v211
	v_and_or_b32 v246, v246, 15, v84
	v_cmp_gt_i32_e32 vcc, s11, v244
	s_nop 1
	v_cndmask_b32_e32 v245, v246, v245, vcc
	v_lshlrev_b32_e32 v246, 7, v245
	v_mov_b32_e32 v247, 0
	v_lshl_add_u64 v[246:247], v[192:193], 0, v[246:247]
	global_load_dwordx4 v[162:165], v[246:247], off offset:64
	global_load_dwordx4 v[166:169], v[246:247], off offset:80
	global_load_dwordx4 v[170:173], v[246:247], off offset:16
	global_load_dwordx4 v[174:177], v[246:247], off
	ds_read_b128 v[112:115], v85 offset:12480
	ds_read_b128 v[116:119], v85 offset:12496
	v_add_u32_e32 v242, 12, v198
	v_mad_i64_i32 v[242:243], s[8:9], v242, s15, v[64:65]
	s_waitcnt vmcnt(15)
	v_fmamk_f32 v238, v223, 0x3b800000, v83
	v_mul_f32_e32 v239, 0x4b800000, v238
	v_cmp_gt_f32_e32 vcc, s14, v238
	s_nop 1
	v_cndmask_b32_e32 v238, v238, v239, vcc
	v_rsq_f32_e32 v238, v238
	s_nop 0
	v_mul_f32_e32 v239, 0x45800000, v238
	v_cndmask_b32_e32 v238, v238, v239, vcc
	s_waitcnt lgkmcnt(0)
	v_pk_mul_f32 v[112:113], v[112:113], v[238:239] op_sel_hi:[1,0]
	v_pk_mul_f32 v[114:115], v[114:115], v[238:239] op_sel_hi:[1,0]
	v_pk_mul_f32 v[116:117], v[116:117], v[238:239] op_sel_hi:[1,0]
	v_pk_mul_f32 v[118:119], v[118:119], v[238:239] op_sel_hi:[1,0]
	s_nop 1
	v_mov_b32_dpp v228, v112 quad_perm:[2,3,0,1] row_mask:0xf bank_mask:0xf bound_ctrl:1
	v_mov_b32_dpp v229, v113 quad_perm:[2,3,0,1] row_mask:0xf bank_mask:0xf bound_ctrl:1
	v_mov_b32_dpp v230, v114 quad_perm:[2,3,0,1] row_mask:0xf bank_mask:0xf bound_ctrl:1
	v_mov_b32_dpp v231, v115 quad_perm:[2,3,0,1] row_mask:0xf bank_mask:0xf bound_ctrl:1
	v_mov_b32_dpp v232, v116 quad_perm:[2,3,0,1] row_mask:0xf bank_mask:0xf bound_ctrl:1
	v_mov_b32_dpp v233, v117 quad_perm:[2,3,0,1] row_mask:0xf bank_mask:0xf bound_ctrl:1
	v_mov_b32_dpp v234, v118 quad_perm:[2,3,0,1] row_mask:0xf bank_mask:0xf bound_ctrl:1
	v_mov_b32_dpp v235, v119 quad_perm:[2,3,0,1] row_mask:0xf bank_mask:0xf bound_ctrl:1
	s_and_saveexec_b64 s[8:9], s[6:7]
	v_pk_mul_f32 v[228:229], v[194:195], v[228:229]
	v_pk_mul_f32 v[230:231], v[194:195], v[230:231]
	v_pk_mul_f32 v[232:233], v[194:195], v[232:233]
	v_pk_mul_f32 v[234:235], v[194:195], v[234:235]
	v_pk_mul_f32 v[228:229], v[228:229], v[88:89]
	v_pk_mul_f32 v[230:231], v[230:231], v[90:91]
	v_pk_mul_f32 v[232:233], v[232:233], v[92:93]
	v_pk_mul_f32 v[234:235], v[234:235], v[94:95]
	v_pk_fma_f32 v[112:113], v[112:113], v[100:101], v[228:229]
	v_pk_fma_f32 v[114:115], v[114:115], v[102:103], v[230:231]
	v_pk_fma_f32 v[116:117], v[116:117], v[96:97], v[232:233]
	v_pk_fma_f32 v[118:119], v[118:119], v[98:99], v[234:235]
	s_or_b64 exec, exec, s[8:9]
	v_cvt_pk_bf16_f32 v112, v112, v113
	v_cvt_pk_bf16_f32 v113, v114, v115
	v_cvt_pk_bf16_f32 v114, v116, v117
	v_cvt_pk_bf16_f32 v115, v118, v119
	global_store_dwordx4 v[242:243], v[112:115], off
	v_add_u32_e32 v244, 28, v198
	v_and_b32_e32 v245, 0x1fff, v244
	v_add_u32_e32 v246, 28, v211
	v_and_or_b32 v246, v246, 15, v84
	v_cmp_gt_i32_e32 vcc, s11, v244
	s_nop 1
	v_cndmask_b32_e32 v245, v246, v245, vcc
	v_lshlrev_b32_e32 v246, 7, v245
	v_mov_b32_e32 v247, 0
	v_lshl_add_u64 v[246:247], v[192:193], 0, v[246:247]
	global_load_dwordx4 v[88:91], v[246:247], off offset:64
	global_load_dwordx4 v[92:95], v[246:247], off offset:80
	global_load_dwordx4 v[96:99], v[246:247], off offset:16
	global_load_dwordx4 v[100:103], v[246:247], off
	ds_read_b128 v[104:107], v85 offset:16640
	ds_read_b128 v[108:111], v85 offset:16656
	v_add_u32_e32 v240, 16, v198
	v_mad_i64_i32 v[240:241], s[8:9], v240, s15, v[64:65]
	s_waitcnt vmcnt(15)
	v_fmamk_f32 v236, v224, 0x3b800000, v83
	v_mul_f32_e32 v237, 0x4b800000, v236
	v_cmp_gt_f32_e32 vcc, s14, v236
	s_nop 1
	v_cndmask_b32_e32 v236, v236, v237, vcc
	v_rsq_f32_e32 v236, v236
	s_nop 0
	v_mul_f32_e32 v237, 0x45800000, v236
	v_cndmask_b32_e32 v236, v236, v237, vcc
	s_waitcnt lgkmcnt(0)
	v_pk_mul_f32 v[104:105], v[104:105], v[236:237] op_sel_hi:[1,0]
	v_pk_mul_f32 v[106:107], v[106:107], v[236:237] op_sel_hi:[1,0]
	v_pk_mul_f32 v[108:109], v[108:109], v[236:237] op_sel_hi:[1,0]
	v_pk_mul_f32 v[110:111], v[110:111], v[236:237] op_sel_hi:[1,0]
	s_nop 1
	v_mov_b32_dpp v120, v104 quad_perm:[2,3,0,1] row_mask:0xf bank_mask:0xf bound_ctrl:1
	v_mov_b32_dpp v121, v105 quad_perm:[2,3,0,1] row_mask:0xf bank_mask:0xf bound_ctrl:1
	v_mov_b32_dpp v122, v106 quad_perm:[2,3,0,1] row_mask:0xf bank_mask:0xf bound_ctrl:1
	v_mov_b32_dpp v123, v107 quad_perm:[2,3,0,1] row_mask:0xf bank_mask:0xf bound_ctrl:1
	v_mov_b32_dpp v124, v108 quad_perm:[2,3,0,1] row_mask:0xf bank_mask:0xf bound_ctrl:1
	v_mov_b32_dpp v125, v109 quad_perm:[2,3,0,1] row_mask:0xf bank_mask:0xf bound_ctrl:1
	v_mov_b32_dpp v126, v110 quad_perm:[2,3,0,1] row_mask:0xf bank_mask:0xf bound_ctrl:1
	v_mov_b32_dpp v127, v111 quad_perm:[2,3,0,1] row_mask:0xf bank_mask:0xf bound_ctrl:1
	s_and_saveexec_b64 s[8:9], s[6:7]
	v_pk_mul_f32 v[120:121], v[194:195], v[120:121]
	v_pk_mul_f32 v[122:123], v[194:195], v[122:123]
	v_pk_mul_f32 v[124:125], v[194:195], v[124:125]
	v_pk_mul_f32 v[126:127], v[194:195], v[126:127]
	v_pk_mul_f32 v[120:121], v[120:121], v[130:131]
	v_pk_mul_f32 v[122:123], v[122:123], v[132:133]
	v_pk_mul_f32 v[124:125], v[124:125], v[134:135]
	v_pk_mul_f32 v[126:127], v[126:127], v[136:137]
	v_pk_fma_f32 v[104:105], v[104:105], v[142:143], v[120:121]
	v_pk_fma_f32 v[106:107], v[106:107], v[144:145], v[122:123]
	v_pk_fma_f32 v[108:109], v[108:109], v[138:139], v[124:125]
	v_pk_fma_f32 v[110:111], v[110:111], v[140:141], v[126:127]
	s_or_b64 exec, exec, s[8:9]
	v_cvt_pk_bf16_f32 v104, v104, v105
	v_cvt_pk_bf16_f32 v105, v106, v107
	v_cvt_pk_bf16_f32 v106, v108, v109
	v_cvt_pk_bf16_f32 v107, v110, v111
	global_store_dwordx4 v[240:241], v[104:107], off
	ds_read_b128 v[112:115], v85 offset:20800
	ds_read_b128 v[116:119], v85 offset:20816
	v_add_u32_e32 v242, 20, v198
	v_mad_i64_i32 v[242:243], s[8:9], v242, s15, v[64:65]
	s_waitcnt vmcnt(11)
	v_fmamk_f32 v238, v225, 0x3b800000, v83
	v_mul_f32_e32 v239, 0x4b800000, v238
	v_cmp_gt_f32_e32 vcc, s14, v238
	s_nop 1
	v_cndmask_b32_e32 v238, v238, v239, vcc
	v_rsq_f32_e32 v238, v238
	s_nop 0
	v_mul_f32_e32 v239, 0x45800000, v238
	v_cndmask_b32_e32 v238, v238, v239, vcc
	s_waitcnt lgkmcnt(0)
	v_pk_mul_f32 v[112:113], v[112:113], v[238:239] op_sel_hi:[1,0]
	v_pk_mul_f32 v[114:115], v[114:115], v[238:239] op_sel_hi:[1,0]
	v_pk_mul_f32 v[116:117], v[116:117], v[238:239] op_sel_hi:[1,0]
	v_pk_mul_f32 v[118:119], v[118:119], v[238:239] op_sel_hi:[1,0]
	s_nop 1
	v_mov_b32_dpp v228, v112 quad_perm:[2,3,0,1] row_mask:0xf bank_mask:0xf bound_ctrl:1
	v_mov_b32_dpp v229, v113 quad_perm:[2,3,0,1] row_mask:0xf bank_mask:0xf bound_ctrl:1
	v_mov_b32_dpp v230, v114 quad_perm:[2,3,0,1] row_mask:0xf bank_mask:0xf bound_ctrl:1
	v_mov_b32_dpp v231, v115 quad_perm:[2,3,0,1] row_mask:0xf bank_mask:0xf bound_ctrl:1
	v_mov_b32_dpp v232, v116 quad_perm:[2,3,0,1] row_mask:0xf bank_mask:0xf bound_ctrl:1
	v_mov_b32_dpp v233, v117 quad_perm:[2,3,0,1] row_mask:0xf bank_mask:0xf bound_ctrl:1
	v_mov_b32_dpp v234, v118 quad_perm:[2,3,0,1] row_mask:0xf bank_mask:0xf bound_ctrl:1
	v_mov_b32_dpp v235, v119 quad_perm:[2,3,0,1] row_mask:0xf bank_mask:0xf bound_ctrl:1
	s_and_saveexec_b64 s[8:9], s[6:7]
	v_pk_mul_f32 v[228:229], v[194:195], v[228:229]
	v_pk_mul_f32 v[230:231], v[194:195], v[230:231]
	v_pk_mul_f32 v[232:233], v[194:195], v[232:233]
	v_pk_mul_f32 v[234:235], v[194:195], v[234:235]
	v_pk_mul_f32 v[228:229], v[228:229], v[146:147]
	v_pk_mul_f32 v[230:231], v[230:231], v[148:149]
	v_pk_mul_f32 v[232:233], v[232:233], v[150:151]
	v_pk_mul_f32 v[234:235], v[234:235], v[152:153]
	v_pk_fma_f32 v[112:113], v[112:113], v[158:159], v[228:229]
	v_pk_fma_f32 v[114:115], v[114:115], v[160:161], v[230:231]
	v_pk_fma_f32 v[116:117], v[116:117], v[154:155], v[232:233]
	v_pk_fma_f32 v[118:119], v[118:119], v[156:157], v[234:235]
	s_or_b64 exec, exec, s[8:9]
	v_cvt_pk_bf16_f32 v112, v112, v113
	v_cvt_pk_bf16_f32 v113, v114, v115
	v_cvt_pk_bf16_f32 v114, v116, v117
	v_cvt_pk_bf16_f32 v115, v118, v119
	global_store_dwordx4 v[242:243], v[112:115], off
	ds_read_b128 v[104:107], v85 offset:24960
	ds_read_b128 v[108:111], v85 offset:24976
	v_add_u32_e32 v240, 24, v198
	v_mad_i64_i32 v[240:241], s[8:9], v240, s15, v[64:65]
	s_waitcnt vmcnt(7)
	v_fmamk_f32 v236, v226, 0x3b800000, v83
	v_mul_f32_e32 v237, 0x4b800000, v236
	v_cmp_gt_f32_e32 vcc, s14, v236
	s_nop 1
	v_cndmask_b32_e32 v236, v236, v237, vcc
	v_rsq_f32_e32 v236, v236
	s_nop 0
	v_mul_f32_e32 v237, 0x45800000, v236
	v_cndmask_b32_e32 v236, v236, v237, vcc
	s_waitcnt lgkmcnt(0)
	v_pk_mul_f32 v[104:105], v[104:105], v[236:237] op_sel_hi:[1,0]
	v_pk_mul_f32 v[106:107], v[106:107], v[236:237] op_sel_hi:[1,0]
	v_pk_mul_f32 v[108:109], v[108:109], v[236:237] op_sel_hi:[1,0]
	v_pk_mul_f32 v[110:111], v[110:111], v[236:237] op_sel_hi:[1,0]
	s_nop 1
	v_mov_b32_dpp v120, v104 quad_perm:[2,3,0,1] row_mask:0xf bank_mask:0xf bound_ctrl:1
	v_mov_b32_dpp v121, v105 quad_perm:[2,3,0,1] row_mask:0xf bank_mask:0xf bound_ctrl:1
	v_mov_b32_dpp v122, v106 quad_perm:[2,3,0,1] row_mask:0xf bank_mask:0xf bound_ctrl:1
	v_mov_b32_dpp v123, v107 quad_perm:[2,3,0,1] row_mask:0xf bank_mask:0xf bound_ctrl:1
	v_mov_b32_dpp v124, v108 quad_perm:[2,3,0,1] row_mask:0xf bank_mask:0xf bound_ctrl:1
	v_mov_b32_dpp v125, v109 quad_perm:[2,3,0,1] row_mask:0xf bank_mask:0xf bound_ctrl:1
	v_mov_b32_dpp v126, v110 quad_perm:[2,3,0,1] row_mask:0xf bank_mask:0xf bound_ctrl:1
	v_mov_b32_dpp v127, v111 quad_perm:[2,3,0,1] row_mask:0xf bank_mask:0xf bound_ctrl:1
	s_and_saveexec_b64 s[8:9], s[6:7]
	v_pk_mul_f32 v[120:121], v[194:195], v[120:121]
	v_pk_mul_f32 v[122:123], v[194:195], v[122:123]
	v_pk_mul_f32 v[124:125], v[194:195], v[124:125]
	v_pk_mul_f32 v[126:127], v[194:195], v[126:127]
	v_pk_mul_f32 v[120:121], v[120:121], v[162:163]
	v_pk_mul_f32 v[122:123], v[122:123], v[164:165]
	v_pk_mul_f32 v[124:125], v[124:125], v[166:167]
	v_pk_mul_f32 v[126:127], v[126:127], v[168:169]
	v_pk_fma_f32 v[104:105], v[104:105], v[174:175], v[120:121]
	v_pk_fma_f32 v[106:107], v[106:107], v[176:177], v[122:123]
	v_pk_fma_f32 v[108:109], v[108:109], v[170:171], v[124:125]
	v_pk_fma_f32 v[110:111], v[110:111], v[172:173], v[126:127]
	s_or_b64 exec, exec, s[8:9]
	v_cvt_pk_bf16_f32 v104, v104, v105
	v_cvt_pk_bf16_f32 v105, v106, v107
	v_cvt_pk_bf16_f32 v106, v108, v109
	v_cvt_pk_bf16_f32 v107, v110, v111
	global_store_dwordx4 v[240:241], v[104:107], off
	ds_read_b128 v[112:115], v85 offset:29120
	ds_read_b128 v[116:119], v85 offset:29136
	v_add_u32_e32 v242, 28, v198
	v_mad_i64_i32 v[242:243], s[8:9], v242, s15, v[64:65]
	s_waitcnt vmcnt(3)
	v_fmamk_f32 v238, v227, 0x3b800000, v83
	v_mul_f32_e32 v239, 0x4b800000, v238
	v_cmp_gt_f32_e32 vcc, s14, v238
	s_nop 1
	v_cndmask_b32_e32 v238, v238, v239, vcc
	v_rsq_f32_e32 v238, v238
	s_nop 0
	v_mul_f32_e32 v239, 0x45800000, v238
	v_cndmask_b32_e32 v238, v238, v239, vcc
	s_waitcnt lgkmcnt(0)
	v_pk_mul_f32 v[112:113], v[112:113], v[238:239] op_sel_hi:[1,0]
	v_pk_mul_f32 v[114:115], v[114:115], v[238:239] op_sel_hi:[1,0]
	v_pk_mul_f32 v[116:117], v[116:117], v[238:239] op_sel_hi:[1,0]
	v_pk_mul_f32 v[118:119], v[118:119], v[238:239] op_sel_hi:[1,0]
	s_nop 1
	v_mov_b32_dpp v228, v112 quad_perm:[2,3,0,1] row_mask:0xf bank_mask:0xf bound_ctrl:1
	v_mov_b32_dpp v229, v113 quad_perm:[2,3,0,1] row_mask:0xf bank_mask:0xf bound_ctrl:1
	v_mov_b32_dpp v230, v114 quad_perm:[2,3,0,1] row_mask:0xf bank_mask:0xf bound_ctrl:1
	v_mov_b32_dpp v231, v115 quad_perm:[2,3,0,1] row_mask:0xf bank_mask:0xf bound_ctrl:1
	v_mov_b32_dpp v232, v116 quad_perm:[2,3,0,1] row_mask:0xf bank_mask:0xf bound_ctrl:1
	v_mov_b32_dpp v233, v117 quad_perm:[2,3,0,1] row_mask:0xf bank_mask:0xf bound_ctrl:1
	v_mov_b32_dpp v234, v118 quad_perm:[2,3,0,1] row_mask:0xf bank_mask:0xf bound_ctrl:1
	v_mov_b32_dpp v235, v119 quad_perm:[2,3,0,1] row_mask:0xf bank_mask:0xf bound_ctrl:1
	s_and_saveexec_b64 s[8:9], s[6:7]
	v_pk_mul_f32 v[228:229], v[194:195], v[228:229]
	v_pk_mul_f32 v[230:231], v[194:195], v[230:231]
	v_pk_mul_f32 v[232:233], v[194:195], v[232:233]
	v_pk_mul_f32 v[234:235], v[194:195], v[234:235]
	v_pk_mul_f32 v[228:229], v[228:229], v[88:89]
	v_pk_mul_f32 v[230:231], v[230:231], v[90:91]
	v_pk_mul_f32 v[232:233], v[232:233], v[92:93]
	v_pk_mul_f32 v[234:235], v[234:235], v[94:95]
	v_pk_fma_f32 v[112:113], v[112:113], v[100:101], v[228:229]
	v_pk_fma_f32 v[114:115], v[114:115], v[102:103], v[230:231]
	v_pk_fma_f32 v[116:117], v[116:117], v[96:97], v[232:233]
	v_pk_fma_f32 v[118:119], v[118:119], v[98:99], v[234:235]
	s_or_b64 exec, exec, s[8:9]
	v_cvt_pk_bf16_f32 v112, v112, v113
	v_cvt_pk_bf16_f32 v113, v114, v115
	v_cvt_pk_bf16_f32 v114, v116, v117
	v_cvt_pk_bf16_f32 v115, v118, v119
	global_store_dwordx4 v[242:243], v[112:115], off
.LBB0_364:
	s_waitcnt lgkmcnt(0)
	s_barrier
	ds_write2_b32 v219, v56, v60 offset1:16
	v_add_u32_e32 v56, 0x400, v219
	ds_write2_b32 v56, v57, v61 offset0:4 offset1:20
	v_add_u32_e32 v57, 0x800, v219
	ds_write2_b32 v57, v58, v62 offset0:8 offset1:24
	v_add_u32_e32 v58, 0xc00, v219
	ds_write2_b32 v58, v59, v63 offset0:12 offset1:28
	v_add_u32_e32 v59, 0x4000, v219
	ds_write2_b32 v59, v48, v52 offset0:64 offset1:80
	v_add_u32_e32 v48, 0x4400, v219
	ds_write2_b32 v48, v49, v53 offset0:68 offset1:84
	v_add_u32_e32 v49, 0x4800, v219
	ds_write2_b32 v49, v50, v54 offset0:72 offset1:88
	v_add_u32_e32 v50, 0x4c00, v219
	ds_write2_b32 v50, v51, v55 offset0:76 offset1:92
	v_add_u32_e32 v51, 0x8000, v219
	ds_write2_b32 v51, v32, v44 offset0:128 offset1:144
	v_add_u32_e32 v32, 0x8400, v219
	ds_write2_b32 v32, v33, v45 offset0:132 offset1:148
	v_add_u32_e32 v33, 0x8800, v219
	ds_write2_b32 v33, v34, v46 offset0:136 offset1:152
	v_add_u32_e32 v34, 0x8c00, v219
	ds_write2_b32 v34, v35, v47 offset0:140 offset1:156
	v_add_u32_e32 v35, 0xc000, v219
	ds_write2_b32 v35, v0, v12 offset0:192 offset1:208
	v_add_u32_e32 v0, 0xc400, v219
	ds_write2_b32 v0, v1, v13 offset0:196 offset1:212
	v_add_u32_e32 v1, 0xc800, v219
	ds_write2_b32 v1, v2, v14 offset0:200 offset1:216
	v_add_u32_e32 v2, 0xcc00, v219
	ds_write2_b32 v2, v3, v15 offset0:204 offset1:220
	ds_write2_b32 v219, v16, v36 offset0:128 offset1:144
	ds_write2_b32 v56, v17, v37 offset0:132 offset1:148
	ds_write2_b32 v57, v18, v38 offset0:136 offset1:152
	ds_write2_b32 v58, v19, v39 offset0:140 offset1:156
	ds_write2_b32 v59, v20, v40 offset0:192 offset1:208
	ds_write2_b32 v48, v21, v41 offset0:196 offset1:212
	ds_write2_b32 v49, v22, v42 offset0:200 offset1:216
	ds_write2_b32 v50, v23, v43 offset0:204 offset1:220
	ds_write2_b32 v32, v8, v28 offset1:16
	ds_write2_b32 v33, v9, v29 offset0:4 offset1:20
	ds_write2_b32 v34, v10, v30 offset0:8 offset1:24
	v_add_u32_e32 v3, 0x9000, v219
	s_movk_i32 s10, 0x4000
	ds_write2_b32 v3, v11, v31 offset0:12 offset1:28
	ds_write2_b32 v0, v4, v24 offset0:64 offset1:80
	ds_write2_b32 v1, v5, v25 offset0:68 offset1:84
	ds_write2_b32 v2, v6, v26 offset0:72 offset1:88
	v_add_u32_e32 v0, 0xd000, v219
	s_mov_b32 s11, 0
	v_mov_b32_e32 v18, 0x358637bd
	s_mov_b32 s14, 0x800000
	v_mov_b32_e32 v1, 0
	s_movk_i32 s15, 0xa00
	v_mov_b32_e32 v19, 0x400
	v_mov_b32_e32 v20, v212
	ds_write2_b32 v0, v7, v27 offset0:76 offset1:92
	s_waitcnt lgkmcnt(0)
	s_barrier
	v_add_u32_e32 v198, 0x80, v82
	v_add_u32_e32 v244, 0, v198
	v_ashrrev_i32_e32 v245, 31, v244
	v_lshl_add_u64 v[244:245], v[244:245], 2, s[12:13]
	global_load_dword v220, v[244:245], off
	v_add_u32_e32 v244, 4, v198
	v_ashrrev_i32_e32 v245, 31, v244
	v_lshl_add_u64 v[244:245], v[244:245], 2, s[12:13]
	global_load_dword v221, v[244:245], off
	v_add_u32_e32 v244, 8, v198
	v_ashrrev_i32_e32 v245, 31, v244
	v_lshl_add_u64 v[244:245], v[244:245], 2, s[12:13]
	global_load_dword v222, v[244:245], off
	v_add_u32_e32 v244, 12, v198
	v_ashrrev_i32_e32 v245, 31, v244
	v_lshl_add_u64 v[244:245], v[244:245], 2, s[12:13]
	global_load_dword v223, v[244:245], off
	v_add_u32_e32 v244, 16, v198
	v_ashrrev_i32_e32 v245, 31, v244
	v_lshl_add_u64 v[244:245], v[244:245], 2, s[12:13]
	global_load_dword v224, v[244:245], off
	v_add_u32_e32 v244, 20, v198
	v_ashrrev_i32_e32 v245, 31, v244
	v_lshl_add_u64 v[244:245], v[244:245], 2, s[12:13]
	global_load_dword v225, v[244:245], off
	v_add_u32_e32 v244, 24, v198
	v_ashrrev_i32_e32 v245, 31, v244
	v_lshl_add_u64 v[244:245], v[244:245], 2, s[12:13]
	global_load_dword v226, v[244:245], off
	v_add_u32_e32 v244, 28, v198
	v_ashrrev_i32_e32 v245, 31, v244
	v_lshl_add_u64 v[244:245], v[244:245], 2, s[12:13]
	global_load_dword v227, v[244:245], off
	v_add_u32_e32 v244, 0, v198
	v_and_b32_e32 v245, 0x1fff, v244
	v_add_u32_e32 v246, 0, v211
	v_and_or_b32 v246, v246, 15, v19
	v_cmp_gt_i32_e32 vcc, s10, v244
	s_nop 1
	v_cndmask_b32_e32 v245, v246, v245, vcc
	v_lshlrev_b32_e32 v246, 7, v245
	v_mov_b32_e32 v247, 0
	v_lshl_add_u64 v[246:247], v[192:193], 0, v[246:247]
	global_load_dwordx4 v[130:133], v[246:247], off offset:64
	global_load_dwordx4 v[134:137], v[246:247], off offset:80
	global_load_dwordx4 v[138:141], v[246:247], off offset:16
	global_load_dwordx4 v[142:145], v[246:247], off
	v_add_u32_e32 v244, 4, v198
	v_and_b32_e32 v245, 0x1fff, v244
	v_add_u32_e32 v246, 4, v211
	v_and_or_b32 v246, v246, 15, v19
	v_cmp_gt_i32_e32 vcc, s10, v244
	s_nop 1
	v_cndmask_b32_e32 v245, v246, v245, vcc
	v_lshlrev_b32_e32 v246, 7, v245
	v_mov_b32_e32 v247, 0
	v_lshl_add_u64 v[246:247], v[192:193], 0, v[246:247]
	global_load_dwordx4 v[146:149], v[246:247], off offset:64
	global_load_dwordx4 v[150:153], v[246:247], off offset:80
	global_load_dwordx4 v[154:157], v[246:247], off offset:16
	global_load_dwordx4 v[158:161], v[246:247], off
	v_add_u32_e32 v244, 8, v198
	v_and_b32_e32 v245, 0x1fff, v244
	v_add_u32_e32 v246, 8, v211
	v_and_or_b32 v246, v246, 15, v19
	v_cmp_gt_i32_e32 vcc, s10, v244
	s_nop 1
	v_cndmask_b32_e32 v245, v246, v245, vcc
	v_lshlrev_b32_e32 v246, 7, v245
	v_mov_b32_e32 v247, 0
	v_lshl_add_u64 v[246:247], v[192:193], 0, v[246:247]
	global_load_dwordx4 v[162:165], v[246:247], off offset:64
	global_load_dwordx4 v[166:169], v[246:247], off offset:80
	global_load_dwordx4 v[170:173], v[246:247], off offset:16
	global_load_dwordx4 v[174:177], v[246:247], off
	v_add_u32_e32 v244, 12, v198
	v_and_b32_e32 v245, 0x1fff, v244
	v_add_u32_e32 v246, 12, v211
	v_and_or_b32 v246, v246, 15, v19
	v_cmp_gt_i32_e32 vcc, s10, v244
	s_nop 1
	v_cndmask_b32_e32 v245, v246, v245, vcc
	v_lshlrev_b32_e32 v246, 7, v245
	v_mov_b32_e32 v247, 0
	v_lshl_add_u64 v[246:247], v[192:193], 0, v[246:247]
	global_load_dwordx4 v[88:91], v[246:247], off offset:64
	global_load_dwordx4 v[92:95], v[246:247], off offset:80
	global_load_dwordx4 v[96:99], v[246:247], off offset:16
	global_load_dwordx4 v[100:103], v[246:247], off
	ds_read_b128 v[104:107], v20 offset:0
	ds_read_b128 v[108:111], v20 offset:16
	v_add_u32_e32 v240, 0, v198
	v_mad_i64_i32 v[240:241], s[8:9], v240, s15, v[64:65]
	s_waitcnt vmcnt(12)
	v_fmamk_f32 v236, v220, 0x3b800000, v18
	v_mul_f32_e32 v237, 0x4b800000, v236
	v_cmp_gt_f32_e32 vcc, s14, v236
	s_nop 1
	v_cndmask_b32_e32 v236, v236, v237, vcc
	v_rsq_f32_e32 v236, v236
	s_nop 0
	v_mul_f32_e32 v237, 0x45800000, v236
	v_cndmask_b32_e32 v236, v236, v237, vcc
	s_waitcnt lgkmcnt(0)
	v_pk_mul_f32 v[104:105], v[104:105], v[236:237] op_sel_hi:[1,0]
	v_pk_mul_f32 v[106:107], v[106:107], v[236:237] op_sel_hi:[1,0]
	v_pk_mul_f32 v[108:109], v[108:109], v[236:237] op_sel_hi:[1,0]
	v_pk_mul_f32 v[110:111], v[110:111], v[236:237] op_sel_hi:[1,0]
	s_nop 1
	v_mov_b32_dpp v120, v104 quad_perm:[2,3,0,1] row_mask:0xf bank_mask:0xf bound_ctrl:1
	v_mov_b32_dpp v121, v105 quad_perm:[2,3,0,1] row_mask:0xf bank_mask:0xf bound_ctrl:1
	v_mov_b32_dpp v122, v106 quad_perm:[2,3,0,1] row_mask:0xf bank_mask:0xf bound_ctrl:1
	v_mov_b32_dpp v123, v107 quad_perm:[2,3,0,1] row_mask:0xf bank_mask:0xf bound_ctrl:1
	v_mov_b32_dpp v124, v108 quad_perm:[2,3,0,1] row_mask:0xf bank_mask:0xf bound_ctrl:1
	v_mov_b32_dpp v125, v109 quad_perm:[2,3,0,1] row_mask:0xf bank_mask:0xf bound_ctrl:1
	v_mov_b32_dpp v126, v110 quad_perm:[2,3,0,1] row_mask:0xf bank_mask:0xf bound_ctrl:1
	v_mov_b32_dpp v127, v111 quad_perm:[2,3,0,1] row_mask:0xf bank_mask:0xf bound_ctrl:1
	s_and_saveexec_b64 s[8:9], s[6:7]
	v_pk_mul_f32 v[120:121], v[194:195], v[120:121]
	v_pk_mul_f32 v[122:123], v[194:195], v[122:123]
	v_pk_mul_f32 v[124:125], v[194:195], v[124:125]
	v_pk_mul_f32 v[126:127], v[194:195], v[126:127]
	v_pk_mul_f32 v[120:121], v[120:121], v[130:131]
	v_pk_mul_f32 v[122:123], v[122:123], v[132:133]
	v_pk_mul_f32 v[124:125], v[124:125], v[134:135]
	v_pk_mul_f32 v[126:127], v[126:127], v[136:137]
	v_pk_fma_f32 v[104:105], v[104:105], v[142:143], v[120:121]
	v_pk_fma_f32 v[106:107], v[106:107], v[144:145], v[122:123]
	v_pk_fma_f32 v[108:109], v[108:109], v[138:139], v[124:125]
	v_pk_fma_f32 v[110:111], v[110:111], v[140:141], v[126:127]
	s_or_b64 exec, exec, s[8:9]
	v_cvt_pk_bf16_f32 v104, v104, v105
	v_cvt_pk_bf16_f32 v105, v106, v107
	v_cvt_pk_bf16_f32 v106, v108, v109
	v_cvt_pk_bf16_f32 v107, v110, v111
	global_store_dwordx4 v[240:241], v[104:107], off
	v_add_u32_e32 v244, 16, v198
	v_and_b32_e32 v245, 0x1fff, v244
	v_add_u32_e32 v246, 16, v211
	v_and_or_b32 v246, v246, 15, v19
	v_cmp_gt_i32_e32 vcc, s10, v244
	s_nop 1
	v_cndmask_b32_e32 v245, v246, v245, vcc
	v_lshlrev_b32_e32 v246, 7, v245
	v_mov_b32_e32 v247, 0
	v_lshl_add_u64 v[246:247], v[192:193], 0, v[246:247]
	global_load_dwordx4 v[130:133], v[246:247], off offset:64
	global_load_dwordx4 v[134:137], v[246:247], off offset:80
	global_load_dwordx4 v[138:141], v[246:247], off offset:16
	global_load_dwordx4 v[142:145], v[246:247], off
	ds_read_b128 v[112:115], v20 offset:4160
	ds_read_b128 v[116:119], v20 offset:4176
	v_add_u32_e32 v242, 4, v198
	v_mad_i64_i32 v[242:243], s[8:9], v242, s15, v[64:65]
	s_waitcnt vmcnt(13)
	v_fmamk_f32 v238, v221, 0x3b800000, v18
	v_mul_f32_e32 v239, 0x4b800000, v238
	v_cmp_gt_f32_e32 vcc, s14, v238
	s_nop 1
	v_cndmask_b32_e32 v238, v238, v239, vcc
	v_rsq_f32_e32 v238, v238
	s_nop 0
	v_mul_f32_e32 v239, 0x45800000, v238
	v_cndmask_b32_e32 v238, v238, v239, vcc
	s_waitcnt lgkmcnt(0)
	v_pk_mul_f32 v[112:113], v[112:113], v[238:239] op_sel_hi:[1,0]
	v_pk_mul_f32 v[114:115], v[114:115], v[238:239] op_sel_hi:[1,0]
	v_pk_mul_f32 v[116:117], v[116:117], v[238:239] op_sel_hi:[1,0]
	v_pk_mul_f32 v[118:119], v[118:119], v[238:239] op_sel_hi:[1,0]
	s_nop 1
	v_mov_b32_dpp v228, v112 quad_perm:[2,3,0,1] row_mask:0xf bank_mask:0xf bound_ctrl:1
	v_mov_b32_dpp v229, v113 quad_perm:[2,3,0,1] row_mask:0xf bank_mask:0xf bound_ctrl:1
	v_mov_b32_dpp v230, v114 quad_perm:[2,3,0,1] row_mask:0xf bank_mask:0xf bound_ctrl:1
	v_mov_b32_dpp v231, v115 quad_perm:[2,3,0,1] row_mask:0xf bank_mask:0xf bound_ctrl:1
	v_mov_b32_dpp v232, v116 quad_perm:[2,3,0,1] row_mask:0xf bank_mask:0xf bound_ctrl:1
	v_mov_b32_dpp v233, v117 quad_perm:[2,3,0,1] row_mask:0xf bank_mask:0xf bound_ctrl:1
	v_mov_b32_dpp v234, v118 quad_perm:[2,3,0,1] row_mask:0xf bank_mask:0xf bound_ctrl:1
	v_mov_b32_dpp v235, v119 quad_perm:[2,3,0,1] row_mask:0xf bank_mask:0xf bound_ctrl:1
	s_and_saveexec_b64 s[8:9], s[6:7]
	v_pk_mul_f32 v[228:229], v[194:195], v[228:229]
	v_pk_mul_f32 v[230:231], v[194:195], v[230:231]
	v_pk_mul_f32 v[232:233], v[194:195], v[232:233]
	v_pk_mul_f32 v[234:235], v[194:195], v[234:235]
	v_pk_mul_f32 v[228:229], v[228:229], v[146:147]
	v_pk_mul_f32 v[230:231], v[230:231], v[148:149]
	v_pk_mul_f32 v[232:233], v[232:233], v[150:151]
	v_pk_mul_f32 v[234:235], v[234:235], v[152:153]
	v_pk_fma_f32 v[112:113], v[112:113], v[158:159], v[228:229]
	v_pk_fma_f32 v[114:115], v[114:115], v[160:161], v[230:231]
	v_pk_fma_f32 v[116:117], v[116:117], v[154:155], v[232:233]
	v_pk_fma_f32 v[118:119], v[118:119], v[156:157], v[234:235]
	s_or_b64 exec, exec, s[8:9]
	v_cvt_pk_bf16_f32 v112, v112, v113
	v_cvt_pk_bf16_f32 v113, v114, v115
	v_cvt_pk_bf16_f32 v114, v116, v117
	v_cvt_pk_bf16_f32 v115, v118, v119
	global_store_dwordx4 v[242:243], v[112:115], off
	v_add_u32_e32 v244, 20, v198
	v_and_b32_e32 v245, 0x1fff, v244
	v_add_u32_e32 v246, 20, v211
	v_and_or_b32 v246, v246, 15, v19
	v_cmp_gt_i32_e32 vcc, s10, v244
	s_nop 1
	v_cndmask_b32_e32 v245, v246, v245, vcc
	v_lshlrev_b32_e32 v246, 7, v245
	v_mov_b32_e32 v247, 0
	v_lshl_add_u64 v[246:247], v[192:193], 0, v[246:247]
	global_load_dwordx4 v[146:149], v[246:247], off offset:64
	global_load_dwordx4 v[150:153], v[246:247], off offset:80
	global_load_dwordx4 v[154:157], v[246:247], off offset:16
	global_load_dwordx4 v[158:161], v[246:247], off
	ds_read_b128 v[104:107], v20 offset:8320
	ds_read_b128 v[108:111], v20 offset:8336
	v_add_u32_e32 v240, 8, v198
	v_mad_i64_i32 v[240:241], s[8:9], v240, s15, v[64:65]
	s_waitcnt vmcnt(14)
	v_fmamk_f32 v236, v222, 0x3b800000, v18
	v_mul_f32_e32 v237, 0x4b800000, v236
	v_cmp_gt_f32_e32 vcc, s14, v236
	s_nop 1
	v_cndmask_b32_e32 v236, v236, v237, vcc
	v_rsq_f32_e32 v236, v236
	s_nop 0
	v_mul_f32_e32 v237, 0x45800000, v236
	v_cndmask_b32_e32 v236, v236, v237, vcc
	s_waitcnt lgkmcnt(0)
	v_pk_mul_f32 v[104:105], v[104:105], v[236:237] op_sel_hi:[1,0]
	v_pk_mul_f32 v[106:107], v[106:107], v[236:237] op_sel_hi:[1,0]
	v_pk_mul_f32 v[108:109], v[108:109], v[236:237] op_sel_hi:[1,0]
	v_pk_mul_f32 v[110:111], v[110:111], v[236:237] op_sel_hi:[1,0]
	s_nop 1
	v_mov_b32_dpp v120, v104 quad_perm:[2,3,0,1] row_mask:0xf bank_mask:0xf bound_ctrl:1
	v_mov_b32_dpp v121, v105 quad_perm:[2,3,0,1] row_mask:0xf bank_mask:0xf bound_ctrl:1
	v_mov_b32_dpp v122, v106 quad_perm:[2,3,0,1] row_mask:0xf bank_mask:0xf bound_ctrl:1
	v_mov_b32_dpp v123, v107 quad_perm:[2,3,0,1] row_mask:0xf bank_mask:0xf bound_ctrl:1
	v_mov_b32_dpp v124, v108 quad_perm:[2,3,0,1] row_mask:0xf bank_mask:0xf bound_ctrl:1
	v_mov_b32_dpp v125, v109 quad_perm:[2,3,0,1] row_mask:0xf bank_mask:0xf bound_ctrl:1
	v_mov_b32_dpp v126, v110 quad_perm:[2,3,0,1] row_mask:0xf bank_mask:0xf bound_ctrl:1
	v_mov_b32_dpp v127, v111 quad_perm:[2,3,0,1] row_mask:0xf bank_mask:0xf bound_ctrl:1
	s_and_saveexec_b64 s[8:9], s[6:7]
	v_pk_mul_f32 v[120:121], v[194:195], v[120:121]
	v_pk_mul_f32 v[122:123], v[194:195], v[122:123]
	v_pk_mul_f32 v[124:125], v[194:195], v[124:125]
	v_pk_mul_f32 v[126:127], v[194:195], v[126:127]
	v_pk_mul_f32 v[120:121], v[120:121], v[162:163]
	v_pk_mul_f32 v[122:123], v[122:123], v[164:165]
	v_pk_mul_f32 v[124:125], v[124:125], v[166:167]
	v_pk_mul_f32 v[126:127], v[126:127], v[168:169]
	v_pk_fma_f32 v[104:105], v[104:105], v[174:175], v[120:121]
	v_pk_fma_f32 v[106:107], v[106:107], v[176:177], v[122:123]
	v_pk_fma_f32 v[108:109], v[108:109], v[170:171], v[124:125]
	v_pk_fma_f32 v[110:111], v[110:111], v[172:173], v[126:127]
	s_or_b64 exec, exec, s[8:9]
	v_cvt_pk_bf16_f32 v104, v104, v105
	v_cvt_pk_bf16_f32 v105, v106, v107
	v_cvt_pk_bf16_f32 v106, v108, v109
	v_cvt_pk_bf16_f32 v107, v110, v111
	global_store_dwordx4 v[240:241], v[104:107], off
	v_add_u32_e32 v244, 24, v198
	v_and_b32_e32 v245, 0x1fff, v244
	v_add_u32_e32 v246, 24, v211
	v_and_or_b32 v246, v246, 15, v19
	v_cmp_gt_i32_e32 vcc, s10, v244
	s_nop 1
	v_cndmask_b32_e32 v245, v246, v245, vcc
	v_lshlrev_b32_e32 v246, 7, v245
	v_mov_b32_e32 v247, 0
	v_lshl_add_u64 v[246:247], v[192:193], 0, v[246:247]
	global_load_dwordx4 v[162:165], v[246:247], off offset:64
	global_load_dwordx4 v[166:169], v[246:247], off offset:80
	global_load_dwordx4 v[170:173], v[246:247], off offset:16
	global_load_dwordx4 v[174:177], v[246:247], off
	ds_read_b128 v[112:115], v20 offset:12480
	ds_read_b128 v[116:119], v20 offset:12496
	v_add_u32_e32 v242, 12, v198
	v_mad_i64_i32 v[242:243], s[8:9], v242, s15, v[64:65]
	s_waitcnt vmcnt(15)
	v_fmamk_f32 v238, v223, 0x3b800000, v18
	v_mul_f32_e32 v239, 0x4b800000, v238
	v_cmp_gt_f32_e32 vcc, s14, v238
	s_nop 1
	v_cndmask_b32_e32 v238, v238, v239, vcc
	v_rsq_f32_e32 v238, v238
	s_nop 0
	v_mul_f32_e32 v239, 0x45800000, v238
	v_cndmask_b32_e32 v238, v238, v239, vcc
	s_waitcnt lgkmcnt(0)
	v_pk_mul_f32 v[112:113], v[112:113], v[238:239] op_sel_hi:[1,0]
	v_pk_mul_f32 v[114:115], v[114:115], v[238:239] op_sel_hi:[1,0]
	v_pk_mul_f32 v[116:117], v[116:117], v[238:239] op_sel_hi:[1,0]
	v_pk_mul_f32 v[118:119], v[118:119], v[238:239] op_sel_hi:[1,0]
	s_nop 1
	v_mov_b32_dpp v228, v112 quad_perm:[2,3,0,1] row_mask:0xf bank_mask:0xf bound_ctrl:1
	v_mov_b32_dpp v229, v113 quad_perm:[2,3,0,1] row_mask:0xf bank_mask:0xf bound_ctrl:1
	v_mov_b32_dpp v230, v114 quad_perm:[2,3,0,1] row_mask:0xf bank_mask:0xf bound_ctrl:1
	v_mov_b32_dpp v231, v115 quad_perm:[2,3,0,1] row_mask:0xf bank_mask:0xf bound_ctrl:1
	v_mov_b32_dpp v232, v116 quad_perm:[2,3,0,1] row_mask:0xf bank_mask:0xf bound_ctrl:1
	v_mov_b32_dpp v233, v117 quad_perm:[2,3,0,1] row_mask:0xf bank_mask:0xf bound_ctrl:1
	v_mov_b32_dpp v234, v118 quad_perm:[2,3,0,1] row_mask:0xf bank_mask:0xf bound_ctrl:1
	v_mov_b32_dpp v235, v119 quad_perm:[2,3,0,1] row_mask:0xf bank_mask:0xf bound_ctrl:1
	s_and_saveexec_b64 s[8:9], s[6:7]
	v_pk_mul_f32 v[228:229], v[194:195], v[228:229]
	v_pk_mul_f32 v[230:231], v[194:195], v[230:231]
	v_pk_mul_f32 v[232:233], v[194:195], v[232:233]
	v_pk_mul_f32 v[234:235], v[194:195], v[234:235]
	v_pk_mul_f32 v[228:229], v[228:229], v[88:89]
	v_pk_mul_f32 v[230:231], v[230:231], v[90:91]
	v_pk_mul_f32 v[232:233], v[232:233], v[92:93]
	v_pk_mul_f32 v[234:235], v[234:235], v[94:95]
	v_pk_fma_f32 v[112:113], v[112:113], v[100:101], v[228:229]
	v_pk_fma_f32 v[114:115], v[114:115], v[102:103], v[230:231]
	v_pk_fma_f32 v[116:117], v[116:117], v[96:97], v[232:233]
	v_pk_fma_f32 v[118:119], v[118:119], v[98:99], v[234:235]
	s_or_b64 exec, exec, s[8:9]
	v_cvt_pk_bf16_f32 v112, v112, v113
	v_cvt_pk_bf16_f32 v113, v114, v115
	v_cvt_pk_bf16_f32 v114, v116, v117
	v_cvt_pk_bf16_f32 v115, v118, v119
	global_store_dwordx4 v[242:243], v[112:115], off
	v_add_u32_e32 v244, 28, v198
	v_and_b32_e32 v245, 0x1fff, v244
	v_add_u32_e32 v246, 28, v211
	v_and_or_b32 v246, v246, 15, v19
	v_cmp_gt_i32_e32 vcc, s10, v244
	s_nop 1
	v_cndmask_b32_e32 v245, v246, v245, vcc
	v_lshlrev_b32_e32 v246, 7, v245
	v_mov_b32_e32 v247, 0
	v_lshl_add_u64 v[246:247], v[192:193], 0, v[246:247]
	global_load_dwordx4 v[88:91], v[246:247], off offset:64
	global_load_dwordx4 v[92:95], v[246:247], off offset:80
	global_load_dwordx4 v[96:99], v[246:247], off offset:16
	global_load_dwordx4 v[100:103], v[246:247], off
	ds_read_b128 v[104:107], v20 offset:16640
	ds_read_b128 v[108:111], v20 offset:16656
	v_add_u32_e32 v240, 16, v198
	v_mad_i64_i32 v[240:241], s[8:9], v240, s15, v[64:65]
	s_waitcnt vmcnt(15)
	v_fmamk_f32 v236, v224, 0x3b800000, v18
	v_mul_f32_e32 v237, 0x4b800000, v236
	v_cmp_gt_f32_e32 vcc, s14, v236
	s_nop 1
	v_cndmask_b32_e32 v236, v236, v237, vcc
	v_rsq_f32_e32 v236, v236
	s_nop 0
	v_mul_f32_e32 v237, 0x45800000, v236
	v_cndmask_b32_e32 v236, v236, v237, vcc
	s_waitcnt lgkmcnt(0)
	v_pk_mul_f32 v[104:105], v[104:105], v[236:237] op_sel_hi:[1,0]
	v_pk_mul_f32 v[106:107], v[106:107], v[236:237] op_sel_hi:[1,0]
	v_pk_mul_f32 v[108:109], v[108:109], v[236:237] op_sel_hi:[1,0]
	v_pk_mul_f32 v[110:111], v[110:111], v[236:237] op_sel_hi:[1,0]
	s_nop 1
	v_mov_b32_dpp v120, v104 quad_perm:[2,3,0,1] row_mask:0xf bank_mask:0xf bound_ctrl:1
	v_mov_b32_dpp v121, v105 quad_perm:[2,3,0,1] row_mask:0xf bank_mask:0xf bound_ctrl:1
	v_mov_b32_dpp v122, v106 quad_perm:[2,3,0,1] row_mask:0xf bank_mask:0xf bound_ctrl:1
	v_mov_b32_dpp v123, v107 quad_perm:[2,3,0,1] row_mask:0xf bank_mask:0xf bound_ctrl:1
	v_mov_b32_dpp v124, v108 quad_perm:[2,3,0,1] row_mask:0xf bank_mask:0xf bound_ctrl:1
	v_mov_b32_dpp v125, v109 quad_perm:[2,3,0,1] row_mask:0xf bank_mask:0xf bound_ctrl:1
	v_mov_b32_dpp v126, v110 quad_perm:[2,3,0,1] row_mask:0xf bank_mask:0xf bound_ctrl:1
	v_mov_b32_dpp v127, v111 quad_perm:[2,3,0,1] row_mask:0xf bank_mask:0xf bound_ctrl:1
	s_and_saveexec_b64 s[8:9], s[6:7]
	v_pk_mul_f32 v[120:121], v[194:195], v[120:121]
	v_pk_mul_f32 v[122:123], v[194:195], v[122:123]
	v_pk_mul_f32 v[124:125], v[194:195], v[124:125]
	v_pk_mul_f32 v[126:127], v[194:195], v[126:127]
	v_pk_mul_f32 v[120:121], v[120:121], v[130:131]
	v_pk_mul_f32 v[122:123], v[122:123], v[132:133]
	v_pk_mul_f32 v[124:125], v[124:125], v[134:135]
	v_pk_mul_f32 v[126:127], v[126:127], v[136:137]
	v_pk_fma_f32 v[104:105], v[104:105], v[142:143], v[120:121]
	v_pk_fma_f32 v[106:107], v[106:107], v[144:145], v[122:123]
	v_pk_fma_f32 v[108:109], v[108:109], v[138:139], v[124:125]
	v_pk_fma_f32 v[110:111], v[110:111], v[140:141], v[126:127]
	s_or_b64 exec, exec, s[8:9]
	v_cvt_pk_bf16_f32 v104, v104, v105
	v_cvt_pk_bf16_f32 v105, v106, v107
	v_cvt_pk_bf16_f32 v106, v108, v109
	v_cvt_pk_bf16_f32 v107, v110, v111
	global_store_dwordx4 v[240:241], v[104:107], off
	ds_read_b128 v[112:115], v20 offset:20800
	ds_read_b128 v[116:119], v20 offset:20816
	v_add_u32_e32 v242, 20, v198
	v_mad_i64_i32 v[242:243], s[8:9], v242, s15, v[64:65]
	s_waitcnt vmcnt(11)
	v_fmamk_f32 v238, v225, 0x3b800000, v18
	v_mul_f32_e32 v239, 0x4b800000, v238
	v_cmp_gt_f32_e32 vcc, s14, v238
	s_nop 1
	v_cndmask_b32_e32 v238, v238, v239, vcc
	v_rsq_f32_e32 v238, v238
	s_nop 0
	v_mul_f32_e32 v239, 0x45800000, v238
	v_cndmask_b32_e32 v238, v238, v239, vcc
	s_waitcnt lgkmcnt(0)
	v_pk_mul_f32 v[112:113], v[112:113], v[238:239] op_sel_hi:[1,0]
	v_pk_mul_f32 v[114:115], v[114:115], v[238:239] op_sel_hi:[1,0]
	v_pk_mul_f32 v[116:117], v[116:117], v[238:239] op_sel_hi:[1,0]
	v_pk_mul_f32 v[118:119], v[118:119], v[238:239] op_sel_hi:[1,0]
	s_nop 1
	v_mov_b32_dpp v228, v112 quad_perm:[2,3,0,1] row_mask:0xf bank_mask:0xf bound_ctrl:1
	v_mov_b32_dpp v229, v113 quad_perm:[2,3,0,1] row_mask:0xf bank_mask:0xf bound_ctrl:1
	v_mov_b32_dpp v230, v114 quad_perm:[2,3,0,1] row_mask:0xf bank_mask:0xf bound_ctrl:1
	v_mov_b32_dpp v231, v115 quad_perm:[2,3,0,1] row_mask:0xf bank_mask:0xf bound_ctrl:1
	v_mov_b32_dpp v232, v116 quad_perm:[2,3,0,1] row_mask:0xf bank_mask:0xf bound_ctrl:1
	v_mov_b32_dpp v233, v117 quad_perm:[2,3,0,1] row_mask:0xf bank_mask:0xf bound_ctrl:1
	v_mov_b32_dpp v234, v118 quad_perm:[2,3,0,1] row_mask:0xf bank_mask:0xf bound_ctrl:1
	v_mov_b32_dpp v235, v119 quad_perm:[2,3,0,1] row_mask:0xf bank_mask:0xf bound_ctrl:1
	s_and_saveexec_b64 s[8:9], s[6:7]
	v_pk_mul_f32 v[228:229], v[194:195], v[228:229]
	v_pk_mul_f32 v[230:231], v[194:195], v[230:231]
	v_pk_mul_f32 v[232:233], v[194:195], v[232:233]
	v_pk_mul_f32 v[234:235], v[194:195], v[234:235]
	v_pk_mul_f32 v[228:229], v[228:229], v[146:147]
	v_pk_mul_f32 v[230:231], v[230:231], v[148:149]
	v_pk_mul_f32 v[232:233], v[232:233], v[150:151]
	v_pk_mul_f32 v[234:235], v[234:235], v[152:153]
	v_pk_fma_f32 v[112:113], v[112:113], v[158:159], v[228:229]
	v_pk_fma_f32 v[114:115], v[114:115], v[160:161], v[230:231]
	v_pk_fma_f32 v[116:117], v[116:117], v[154:155], v[232:233]
	v_pk_fma_f32 v[118:119], v[118:119], v[156:157], v[234:235]
	s_or_b64 exec, exec, s[8:9]
	v_cvt_pk_bf16_f32 v112, v112, v113
	v_cvt_pk_bf16_f32 v113, v114, v115
	v_cvt_pk_bf16_f32 v114, v116, v117
	v_cvt_pk_bf16_f32 v115, v118, v119
	global_store_dwordx4 v[242:243], v[112:115], off
	ds_read_b128 v[104:107], v20 offset:24960
	ds_read_b128 v[108:111], v20 offset:24976
	v_add_u32_e32 v240, 24, v198
	v_mad_i64_i32 v[240:241], s[8:9], v240, s15, v[64:65]
	s_waitcnt vmcnt(7)
	v_fmamk_f32 v236, v226, 0x3b800000, v18
	v_mul_f32_e32 v237, 0x4b800000, v236
	v_cmp_gt_f32_e32 vcc, s14, v236
	s_nop 1
	v_cndmask_b32_e32 v236, v236, v237, vcc
	v_rsq_f32_e32 v236, v236
	s_nop 0
	v_mul_f32_e32 v237, 0x45800000, v236
	v_cndmask_b32_e32 v236, v236, v237, vcc
	s_waitcnt lgkmcnt(0)
	v_pk_mul_f32 v[104:105], v[104:105], v[236:237] op_sel_hi:[1,0]
	v_pk_mul_f32 v[106:107], v[106:107], v[236:237] op_sel_hi:[1,0]
	v_pk_mul_f32 v[108:109], v[108:109], v[236:237] op_sel_hi:[1,0]
	v_pk_mul_f32 v[110:111], v[110:111], v[236:237] op_sel_hi:[1,0]
	s_nop 1
	v_mov_b32_dpp v120, v104 quad_perm:[2,3,0,1] row_mask:0xf bank_mask:0xf bound_ctrl:1
	v_mov_b32_dpp v121, v105 quad_perm:[2,3,0,1] row_mask:0xf bank_mask:0xf bound_ctrl:1
	v_mov_b32_dpp v122, v106 quad_perm:[2,3,0,1] row_mask:0xf bank_mask:0xf bound_ctrl:1
	v_mov_b32_dpp v123, v107 quad_perm:[2,3,0,1] row_mask:0xf bank_mask:0xf bound_ctrl:1
	v_mov_b32_dpp v124, v108 quad_perm:[2,3,0,1] row_mask:0xf bank_mask:0xf bound_ctrl:1
	v_mov_b32_dpp v125, v109 quad_perm:[2,3,0,1] row_mask:0xf bank_mask:0xf bound_ctrl:1
	v_mov_b32_dpp v126, v110 quad_perm:[2,3,0,1] row_mask:0xf bank_mask:0xf bound_ctrl:1
	v_mov_b32_dpp v127, v111 quad_perm:[2,3,0,1] row_mask:0xf bank_mask:0xf bound_ctrl:1
	s_and_saveexec_b64 s[8:9], s[6:7]
	v_pk_mul_f32 v[120:121], v[194:195], v[120:121]
	v_pk_mul_f32 v[122:123], v[194:195], v[122:123]
	v_pk_mul_f32 v[124:125], v[194:195], v[124:125]
	v_pk_mul_f32 v[126:127], v[194:195], v[126:127]
	v_pk_mul_f32 v[120:121], v[120:121], v[162:163]
	v_pk_mul_f32 v[122:123], v[122:123], v[164:165]
	v_pk_mul_f32 v[124:125], v[124:125], v[166:167]
	v_pk_mul_f32 v[126:127], v[126:127], v[168:169]
	v_pk_fma_f32 v[104:105], v[104:105], v[174:175], v[120:121]
	v_pk_fma_f32 v[106:107], v[106:107], v[176:177], v[122:123]
	v_pk_fma_f32 v[108:109], v[108:109], v[170:171], v[124:125]
	v_pk_fma_f32 v[110:111], v[110:111], v[172:173], v[126:127]
	s_or_b64 exec, exec, s[8:9]
	v_cvt_pk_bf16_f32 v104, v104, v105
	v_cvt_pk_bf16_f32 v105, v106, v107
	v_cvt_pk_bf16_f32 v106, v108, v109
	v_cvt_pk_bf16_f32 v107, v110, v111
	global_store_dwordx4 v[240:241], v[104:107], off
	ds_read_b128 v[112:115], v20 offset:29120
	ds_read_b128 v[116:119], v20 offset:29136
	v_add_u32_e32 v242, 28, v198
	v_mad_i64_i32 v[242:243], s[8:9], v242, s15, v[64:65]
	s_waitcnt vmcnt(3)
	v_fmamk_f32 v238, v227, 0x3b800000, v18
	v_mul_f32_e32 v239, 0x4b800000, v238
	v_cmp_gt_f32_e32 vcc, s14, v238
	s_nop 1
	v_cndmask_b32_e32 v238, v238, v239, vcc
	v_rsq_f32_e32 v238, v238
	s_nop 0
	v_mul_f32_e32 v239, 0x45800000, v238
	v_cndmask_b32_e32 v238, v238, v239, vcc
	s_waitcnt lgkmcnt(0)
	v_pk_mul_f32 v[112:113], v[112:113], v[238:239] op_sel_hi:[1,0]
	v_pk_mul_f32 v[114:115], v[114:115], v[238:239] op_sel_hi:[1,0]
	v_pk_mul_f32 v[116:117], v[116:117], v[238:239] op_sel_hi:[1,0]
	v_pk_mul_f32 v[118:119], v[118:119], v[238:239] op_sel_hi:[1,0]
	s_nop 1
	v_mov_b32_dpp v228, v112 quad_perm:[2,3,0,1] row_mask:0xf bank_mask:0xf bound_ctrl:1
	v_mov_b32_dpp v229, v113 quad_perm:[2,3,0,1] row_mask:0xf bank_mask:0xf bound_ctrl:1
	v_mov_b32_dpp v230, v114 quad_perm:[2,3,0,1] row_mask:0xf bank_mask:0xf bound_ctrl:1
	v_mov_b32_dpp v231, v115 quad_perm:[2,3,0,1] row_mask:0xf bank_mask:0xf bound_ctrl:1
	v_mov_b32_dpp v232, v116 quad_perm:[2,3,0,1] row_mask:0xf bank_mask:0xf bound_ctrl:1
	v_mov_b32_dpp v233, v117 quad_perm:[2,3,0,1] row_mask:0xf bank_mask:0xf bound_ctrl:1
	v_mov_b32_dpp v234, v118 quad_perm:[2,3,0,1] row_mask:0xf bank_mask:0xf bound_ctrl:1
	v_mov_b32_dpp v235, v119 quad_perm:[2,3,0,1] row_mask:0xf bank_mask:0xf bound_ctrl:1
	s_and_saveexec_b64 s[8:9], s[6:7]
	v_pk_mul_f32 v[228:229], v[194:195], v[228:229]
	v_pk_mul_f32 v[230:231], v[194:195], v[230:231]
	v_pk_mul_f32 v[232:233], v[194:195], v[232:233]
	v_pk_mul_f32 v[234:235], v[194:195], v[234:235]
	v_pk_mul_f32 v[228:229], v[228:229], v[88:89]
	v_pk_mul_f32 v[230:231], v[230:231], v[90:91]
	v_pk_mul_f32 v[232:233], v[232:233], v[92:93]
	v_pk_mul_f32 v[234:235], v[234:235], v[94:95]
	v_pk_fma_f32 v[112:113], v[112:113], v[100:101], v[228:229]
	v_pk_fma_f32 v[114:115], v[114:115], v[102:103], v[230:231]
	v_pk_fma_f32 v[116:117], v[116:117], v[96:97], v[232:233]
	v_pk_fma_f32 v[118:119], v[118:119], v[98:99], v[234:235]
	s_or_b64 exec, exec, s[8:9]
	v_cvt_pk_bf16_f32 v112, v112, v113
	v_cvt_pk_bf16_f32 v113, v114, v115
	v_cvt_pk_bf16_f32 v114, v116, v117
	v_cvt_pk_bf16_f32 v115, v118, v119
	global_store_dwordx4 v[242:243], v[112:115], off

.LBB0_388:
	s_or_b64 exec, exec, s[8:9]
	s_waitcnt vmcnt(0) lgkmcnt(0)
	s_barrier
	ds_write2_b32 v219, v112, v124 offset1:16
	v_add_u32_e32 v112, 0x400, v219
	ds_write2_b32 v112, v113, v125 offset0:4 offset1:20
	v_add_u32_e32 v113, 0x800, v219
	ds_write2_b32 v113, v114, v126 offset0:8 offset1:24
	v_add_u32_e32 v114, 0xc00, v219
	ds_write2_b32 v114, v115, v127 offset0:12 offset1:28
	v_add_u32_e32 v115, 0x4000, v219
	ds_write2_b32 v115, v80, v88 offset0:64 offset1:80
	v_add_u32_e32 v80, 0x4400, v219
	ds_write2_b32 v80, v81, v89 offset0:68 offset1:84
	v_add_u32_e32 v81, 0x4800, v219
	ds_write2_b32 v81, v82, v90 offset0:72 offset1:88
	v_add_u32_e32 v82, 0x4c00, v219
	ds_write2_b32 v82, v83, v91 offset0:76 offset1:92
	v_add_u32_e32 v83, 0x8000, v219
	ds_write2_b32 v83, v72, v76 offset0:128 offset1:144
	v_add_u32_e32 v72, 0x8400, v219
	ds_write2_b32 v72, v73, v77 offset0:132 offset1:148
	v_add_u32_e32 v73, 0x8800, v219
	ds_write2_b32 v73, v74, v78 offset0:136 offset1:152
	v_add_u32_e32 v74, 0x8c00, v219
	ds_write2_b32 v74, v75, v79 offset0:140 offset1:156
	v_add_u32_e32 v75, 0xc000, v219
	ds_write2_b32 v75, v64, v68 offset0:192 offset1:208
	v_add_u32_e32 v64, 0xc400, v219
	ds_write2_b32 v64, v65, v69 offset0:196 offset1:212
	v_add_u32_e32 v65, 0xc800, v219
	ds_write2_b32 v65, v66, v70 offset0:200 offset1:216
	v_add_u32_e32 v66, 0xcc00, v219
	ds_write2_b32 v66, v67, v71 offset0:204 offset1:220
	ds_write2_b32 v219, v96, v116 offset0:128 offset1:144
	ds_write2_b32 v112, v97, v117 offset0:132 offset1:148
	ds_write2_b32 v113, v98, v118 offset0:136 offset1:152
	ds_write2_b32 v114, v99, v119 offset0:140 offset1:156
	ds_write2_b32 v115, v100, v120 offset0:192 offset1:208
	ds_write2_b32 v80, v101, v121 offset0:196 offset1:212
	ds_write2_b32 v81, v102, v122 offset0:200 offset1:216
	ds_write2_b32 v82, v103, v123 offset0:204 offset1:220
	ds_write2_b32 v72, v92, v108 offset1:16
	ds_write2_b32 v73, v93, v109 offset0:4 offset1:20
	ds_write2_b32 v74, v94, v110 offset0:8 offset1:24
	v_add_u32_e32 v67, 0x9000, v219
	v_or_b32_e32 v130, s20, v216
	ds_write2_b32 v67, v95, v111 offset0:12 offset1:28
	ds_write2_b32 v64, v84, v104 offset0:64 offset1:80
	ds_write2_b32 v65, v85, v105 offset0:68 offset1:84
	ds_write2_b32 v66, v86, v106 offset0:72 offset1:88
	v_add_u32_e32 v64, 0xd000, v219
	ds_write2_b32 v64, v87, v107 offset0:76 offset1:92
	v_ashrrev_i32_e32 v64, 5, v130
	v_or_b32_e32 v64, v64, v215
	s_mov_b32 s4, 0x66666667
	v_mul_hi_i32 v65, v64, s4
	v_lshrrev_b32_e32 v66, 31, v65
	v_ashrrev_i32_e32 v65, 1, v65
	v_add_u32_e32 v65, v65, v66
	v_lshl_add_u32 v65, v65, 2, v65
	v_sub_u32_e32 v64, v64, v65
	v_ashrrev_i32_e32 v131, 31, v130
	v_add_u32_e32 v128, s14, v213
	s_movk_i32 s3, 0x4000
	v_cmp_eq_u32_e64 s[8:9], 4, v64
	v_lshl_add_u64 v[64:65], v[130:131], 1, v[196:197]
	s_mov_b32 s4, 0
	v_mov_b32_e32 v84, 0x358637bd
	s_mov_b32 s5, 0x800000
	v_mov_b32_e32 v67, 0
	s_movk_i32 s15, 0xa00
	v_mov_b32_e32 v85, 0x400
	v_mov_b32_e32 v86, v211
	s_waitcnt lgkmcnt(0)
	s_barrier
	v_add_u32_e32 v198, v128, v211
	v_add_u32_e32 v244, 0, v198
	v_ashrrev_i32_e32 v245, 31, v244
	v_lshl_add_u64 v[244:245], v[244:245], 2, s[12:13]
	global_load_dword v220, v[244:245], off
	v_add_u32_e32 v244, 4, v198
	v_ashrrev_i32_e32 v245, 31, v244
	v_lshl_add_u64 v[244:245], v[244:245], 2, s[12:13]
	global_load_dword v221, v[244:245], off
	v_add_u32_e32 v244, 8, v198
	v_ashrrev_i32_e32 v245, 31, v244
	v_lshl_add_u64 v[244:245], v[244:245], 2, s[12:13]
	global_load_dword v222, v[244:245], off
	v_add_u32_e32 v244, 12, v198
	v_ashrrev_i32_e32 v245, 31, v244
	v_lshl_add_u64 v[244:245], v[244:245], 2, s[12:13]
	global_load_dword v223, v[244:245], off
	v_add_u32_e32 v244, 16, v198
	v_ashrrev_i32_e32 v245, 31, v244
	v_lshl_add_u64 v[244:245], v[244:245], 2, s[12:13]
	global_load_dword v224, v[244:245], off
	v_add_u32_e32 v244, 20, v198
	v_ashrrev_i32_e32 v245, 31, v244
	v_lshl_add_u64 v[244:245], v[244:245], 2, s[12:13]
	global_load_dword v225, v[244:245], off
	v_add_u32_e32 v244, 24, v198
	v_ashrrev_i32_e32 v245, 31, v244
	v_lshl_add_u64 v[244:245], v[244:245], 2, s[12:13]
	global_load_dword v226, v[244:245], off
	v_add_u32_e32 v244, 28, v198
	v_ashrrev_i32_e32 v245, 31, v244
	v_lshl_add_u64 v[244:245], v[244:245], 2, s[12:13]
	global_load_dword v227, v[244:245], off
	v_add_u32_e32 v244, 0, v198
	v_and_b32_e32 v245, 0x1fff, v244
	v_add_u32_e32 v246, 0, v211
	v_and_or_b32 v246, v246, 15, v85
	v_cmp_gt_i32_e32 vcc, s3, v244
	s_nop 1
	v_cndmask_b32_e32 v245, v246, v245, vcc
	v_lshlrev_b32_e32 v246, 7, v245
	v_mov_b32_e32 v247, 0
	v_lshl_add_u64 v[246:247], v[192:193], 0, v[246:247]
	global_load_dwordx4 v[130:133], v[246:247], off offset:64
	global_load_dwordx4 v[134:137], v[246:247], off offset:80
	global_load_dwordx4 v[138:141], v[246:247], off offset:16
	global_load_dwordx4 v[142:145], v[246:247], off
	v_add_u32_e32 v244, 4, v198
	v_and_b32_e32 v245, 0x1fff, v244
	v_add_u32_e32 v246, 4, v211
	v_and_or_b32 v246, v246, 15, v85
	v_cmp_gt_i32_e32 vcc, s3, v244
	s_nop 1
	v_cndmask_b32_e32 v245, v246, v245, vcc
	v_lshlrev_b32_e32 v246, 7, v245
	v_mov_b32_e32 v247, 0
	v_lshl_add_u64 v[246:247], v[192:193], 0, v[246:247]
	global_load_dwordx4 v[146:149], v[246:247], off offset:64
	global_load_dwordx4 v[150:153], v[246:247], off offset:80
	global_load_dwordx4 v[154:157], v[246:247], off offset:16
	global_load_dwordx4 v[158:161], v[246:247], off
	v_add_u32_e32 v244, 8, v198
	v_and_b32_e32 v245, 0x1fff, v244
	v_add_u32_e32 v246, 8, v211
	v_and_or_b32 v246, v246, 15, v85
	v_cmp_gt_i32_e32 vcc, s3, v244
	s_nop 1
	v_cndmask_b32_e32 v245, v246, v245, vcc
	v_lshlrev_b32_e32 v246, 7, v245
	v_mov_b32_e32 v247, 0
	v_lshl_add_u64 v[246:247], v[192:193], 0, v[246:247]
	global_load_dwordx4 v[162:165], v[246:247], off offset:64
	global_load_dwordx4 v[166:169], v[246:247], off offset:80
	global_load_dwordx4 v[170:173], v[246:247], off offset:16
	global_load_dwordx4 v[174:177], v[246:247], off
	v_add_u32_e32 v244, 12, v198
	v_and_b32_e32 v245, 0x1fff, v244
	v_add_u32_e32 v246, 12, v211
	v_and_or_b32 v246, v246, 15, v85
	v_cmp_gt_i32_e32 vcc, s3, v244
	s_nop 1
	v_cndmask_b32_e32 v245, v246, v245, vcc
	v_lshlrev_b32_e32 v246, 7, v245
	v_mov_b32_e32 v247, 0
	v_lshl_add_u64 v[246:247], v[192:193], 0, v[246:247]
	global_load_dwordx4 v[88:91], v[246:247], off offset:64
	global_load_dwordx4 v[92:95], v[246:247], off offset:80
	global_load_dwordx4 v[96:99], v[246:247], off offset:16
	global_load_dwordx4 v[100:103], v[246:247], off
	ds_read_b128 v[104:107], v212 offset:0
	ds_read_b128 v[108:111], v212 offset:16
	v_add_u32_e32 v240, 0, v198
	v_mad_i64_i32 v[240:241], s[10:11], v240, s15, v[64:65]
	s_waitcnt vmcnt(12)
	v_fmamk_f32 v236, v220, 0x3b800000, v84
	v_mul_f32_e32 v237, 0x4b800000, v236
	v_cmp_gt_f32_e32 vcc, s5, v236
	s_nop 1
	v_cndmask_b32_e32 v236, v236, v237, vcc
	v_rsq_f32_e32 v236, v236
	s_nop 0
	v_mul_f32_e32 v237, 0x45800000, v236
	v_cndmask_b32_e32 v236, v236, v237, vcc
	s_waitcnt lgkmcnt(0)
	v_pk_mul_f32 v[104:105], v[104:105], v[236:237] op_sel_hi:[1,0]
	v_pk_mul_f32 v[106:107], v[106:107], v[236:237] op_sel_hi:[1,0]
	v_pk_mul_f32 v[108:109], v[108:109], v[236:237] op_sel_hi:[1,0]
	v_pk_mul_f32 v[110:111], v[110:111], v[236:237] op_sel_hi:[1,0]
	s_nop 1
	v_mov_b32_dpp v120, v104 quad_perm:[2,3,0,1] row_mask:0xf bank_mask:0xf bound_ctrl:1
	v_mov_b32_dpp v121, v105 quad_perm:[2,3,0,1] row_mask:0xf bank_mask:0xf bound_ctrl:1
	v_mov_b32_dpp v122, v106 quad_perm:[2,3,0,1] row_mask:0xf bank_mask:0xf bound_ctrl:1
	v_mov_b32_dpp v123, v107 quad_perm:[2,3,0,1] row_mask:0xf bank_mask:0xf bound_ctrl:1
	v_mov_b32_dpp v124, v108 quad_perm:[2,3,0,1] row_mask:0xf bank_mask:0xf bound_ctrl:1
	v_mov_b32_dpp v125, v109 quad_perm:[2,3,0,1] row_mask:0xf bank_mask:0xf bound_ctrl:1
	v_mov_b32_dpp v126, v110 quad_perm:[2,3,0,1] row_mask:0xf bank_mask:0xf bound_ctrl:1
	v_mov_b32_dpp v127, v111 quad_perm:[2,3,0,1] row_mask:0xf bank_mask:0xf bound_ctrl:1
	s_and_saveexec_b64 s[10:11], s[8:9]
	v_pk_mul_f32 v[120:121], v[194:195], v[120:121]
	v_pk_mul_f32 v[122:123], v[194:195], v[122:123]
	v_pk_mul_f32 v[124:125], v[194:195], v[124:125]
	v_pk_mul_f32 v[126:127], v[194:195], v[126:127]
	v_pk_mul_f32 v[120:121], v[120:121], v[130:131]
	v_pk_mul_f32 v[122:123], v[122:123], v[132:133]
	v_pk_mul_f32 v[124:125], v[124:125], v[134:135]
	v_pk_mul_f32 v[126:127], v[126:127], v[136:137]
	v_pk_fma_f32 v[104:105], v[104:105], v[142:143], v[120:121]
	v_pk_fma_f32 v[106:107], v[106:107], v[144:145], v[122:123]
	v_pk_fma_f32 v[108:109], v[108:109], v[138:139], v[124:125]
	v_pk_fma_f32 v[110:111], v[110:111], v[140:141], v[126:127]
	s_or_b64 exec, exec, s[10:11]
	v_cvt_pk_bf16_f32 v104, v104, v105
	v_cvt_pk_bf16_f32 v105, v106, v107
	v_cvt_pk_bf16_f32 v106, v108, v109
	v_cvt_pk_bf16_f32 v107, v110, v111
	global_store_dwordx4 v[240:241], v[104:107], off
	v_add_u32_e32 v244, 16, v198
	v_and_b32_e32 v245, 0x1fff, v244
	v_add_u32_e32 v246, 16, v211
	v_and_or_b32 v246, v246, 15, v85
	v_cmp_gt_i32_e32 vcc, s3, v244
	s_nop 1
	v_cndmask_b32_e32 v245, v246, v245, vcc
	v_lshlrev_b32_e32 v246, 7, v245
	v_mov_b32_e32 v247, 0
	v_lshl_add_u64 v[246:247], v[192:193], 0, v[246:247]
	global_load_dwordx4 v[130:133], v[246:247], off offset:64
	global_load_dwordx4 v[134:137], v[246:247], off offset:80
	global_load_dwordx4 v[138:141], v[246:247], off offset:16
	global_load_dwordx4 v[142:145], v[246:247], off
	ds_read_b128 v[112:115], v212 offset:4160
	ds_read_b128 v[116:119], v212 offset:4176
	v_add_u32_e32 v242, 4, v198
	v_mad_i64_i32 v[242:243], s[10:11], v242, s15, v[64:65]
	s_waitcnt vmcnt(13)
	v_fmamk_f32 v238, v221, 0x3b800000, v84
	v_mul_f32_e32 v239, 0x4b800000, v238
	v_cmp_gt_f32_e32 vcc, s5, v238
	s_nop 1
	v_cndmask_b32_e32 v238, v238, v239, vcc
	v_rsq_f32_e32 v238, v238
	s_nop 0
	v_mul_f32_e32 v239, 0x45800000, v238
	v_cndmask_b32_e32 v238, v238, v239, vcc
	s_waitcnt lgkmcnt(0)
	v_pk_mul_f32 v[112:113], v[112:113], v[238:239] op_sel_hi:[1,0]
	v_pk_mul_f32 v[114:115], v[114:115], v[238:239] op_sel_hi:[1,0]
	v_pk_mul_f32 v[116:117], v[116:117], v[238:239] op_sel_hi:[1,0]
	v_pk_mul_f32 v[118:119], v[118:119], v[238:239] op_sel_hi:[1,0]
	s_nop 1
	v_mov_b32_dpp v228, v112 quad_perm:[2,3,0,1] row_mask:0xf bank_mask:0xf bound_ctrl:1
	v_mov_b32_dpp v229, v113 quad_perm:[2,3,0,1] row_mask:0xf bank_mask:0xf bound_ctrl:1
	v_mov_b32_dpp v230, v114 quad_perm:[2,3,0,1] row_mask:0xf bank_mask:0xf bound_ctrl:1
	v_mov_b32_dpp v231, v115 quad_perm:[2,3,0,1] row_mask:0xf bank_mask:0xf bound_ctrl:1
	v_mov_b32_dpp v232, v116 quad_perm:[2,3,0,1] row_mask:0xf bank_mask:0xf bound_ctrl:1
	v_mov_b32_dpp v233, v117 quad_perm:[2,3,0,1] row_mask:0xf bank_mask:0xf bound_ctrl:1
	v_mov_b32_dpp v234, v118 quad_perm:[2,3,0,1] row_mask:0xf bank_mask:0xf bound_ctrl:1
	v_mov_b32_dpp v235, v119 quad_perm:[2,3,0,1] row_mask:0xf bank_mask:0xf bound_ctrl:1
	s_and_saveexec_b64 s[10:11], s[8:9]
	v_pk_mul_f32 v[228:229], v[194:195], v[228:229]
	v_pk_mul_f32 v[230:231], v[194:195], v[230:231]
	v_pk_mul_f32 v[232:233], v[194:195], v[232:233]
	v_pk_mul_f32 v[234:235], v[194:195], v[234:235]
	v_pk_mul_f32 v[228:229], v[228:229], v[146:147]
	v_pk_mul_f32 v[230:231], v[230:231], v[148:149]
	v_pk_mul_f32 v[232:233], v[232:233], v[150:151]
	v_pk_mul_f32 v[234:235], v[234:235], v[152:153]
	v_pk_fma_f32 v[112:113], v[112:113], v[158:159], v[228:229]
	v_pk_fma_f32 v[114:115], v[114:115], v[160:161], v[230:231]
	v_pk_fma_f32 v[116:117], v[116:117], v[154:155], v[232:233]
	v_pk_fma_f32 v[118:119], v[118:119], v[156:157], v[234:235]
	s_or_b64 exec, exec, s[10:11]
	v_cvt_pk_bf16_f32 v112, v112, v113
	v_cvt_pk_bf16_f32 v113, v114, v115
	v_cvt_pk_bf16_f32 v114, v116, v117
	v_cvt_pk_bf16_f32 v115, v118, v119
	global_store_dwordx4 v[242:243], v[112:115], off
	v_add_u32_e32 v244, 20, v198
	v_and_b32_e32 v245, 0x1fff, v244
	v_add_u32_e32 v246, 20, v211
	v_and_or_b32 v246, v246, 15, v85
	v_cmp_gt_i32_e32 vcc, s3, v244
	s_nop 1
	v_cndmask_b32_e32 v245, v246, v245, vcc
	v_lshlrev_b32_e32 v246, 7, v245
	v_mov_b32_e32 v247, 0
	v_lshl_add_u64 v[246:247], v[192:193], 0, v[246:247]
	global_load_dwordx4 v[146:149], v[246:247], off offset:64
	global_load_dwordx4 v[150:153], v[246:247], off offset:80
	global_load_dwordx4 v[154:157], v[246:247], off offset:16
	global_load_dwordx4 v[158:161], v[246:247], off
	ds_read_b128 v[104:107], v212 offset:8320
	ds_read_b128 v[108:111], v212 offset:8336
	v_add_u32_e32 v240, 8, v198
	v_mad_i64_i32 v[240:241], s[10:11], v240, s15, v[64:65]
	s_waitcnt vmcnt(14)
	v_fmamk_f32 v236, v222, 0x3b800000, v84
	v_mul_f32_e32 v237, 0x4b800000, v236
	v_cmp_gt_f32_e32 vcc, s5, v236
	s_nop 1
	v_cndmask_b32_e32 v236, v236, v237, vcc
	v_rsq_f32_e32 v236, v236
	s_nop 0
	v_mul_f32_e32 v237, 0x45800000, v236
	v_cndmask_b32_e32 v236, v236, v237, vcc
	s_waitcnt lgkmcnt(0)
	v_pk_mul_f32 v[104:105], v[104:105], v[236:237] op_sel_hi:[1,0]
	v_pk_mul_f32 v[106:107], v[106:107], v[236:237] op_sel_hi:[1,0]
	v_pk_mul_f32 v[108:109], v[108:109], v[236:237] op_sel_hi:[1,0]
	v_pk_mul_f32 v[110:111], v[110:111], v[236:237] op_sel_hi:[1,0]
	s_nop 1
	v_mov_b32_dpp v120, v104 quad_perm:[2,3,0,1] row_mask:0xf bank_mask:0xf bound_ctrl:1
	v_mov_b32_dpp v121, v105 quad_perm:[2,3,0,1] row_mask:0xf bank_mask:0xf bound_ctrl:1
	v_mov_b32_dpp v122, v106 quad_perm:[2,3,0,1] row_mask:0xf bank_mask:0xf bound_ctrl:1
	v_mov_b32_dpp v123, v107 quad_perm:[2,3,0,1] row_mask:0xf bank_mask:0xf bound_ctrl:1
	v_mov_b32_dpp v124, v108 quad_perm:[2,3,0,1] row_mask:0xf bank_mask:0xf bound_ctrl:1
	v_mov_b32_dpp v125, v109 quad_perm:[2,3,0,1] row_mask:0xf bank_mask:0xf bound_ctrl:1
	v_mov_b32_dpp v126, v110 quad_perm:[2,3,0,1] row_mask:0xf bank_mask:0xf bound_ctrl:1
	v_mov_b32_dpp v127, v111 quad_perm:[2,3,0,1] row_mask:0xf bank_mask:0xf bound_ctrl:1
	s_and_saveexec_b64 s[10:11], s[8:9]
	v_pk_mul_f32 v[120:121], v[194:195], v[120:121]
	v_pk_mul_f32 v[122:123], v[194:195], v[122:123]
	v_pk_mul_f32 v[124:125], v[194:195], v[124:125]
	v_pk_mul_f32 v[126:127], v[194:195], v[126:127]
	v_pk_mul_f32 v[120:121], v[120:121], v[162:163]
	v_pk_mul_f32 v[122:123], v[122:123], v[164:165]
	v_pk_mul_f32 v[124:125], v[124:125], v[166:167]
	v_pk_mul_f32 v[126:127], v[126:127], v[168:169]
	v_pk_fma_f32 v[104:105], v[104:105], v[174:175], v[120:121]
	v_pk_fma_f32 v[106:107], v[106:107], v[176:177], v[122:123]
	v_pk_fma_f32 v[108:109], v[108:109], v[170:171], v[124:125]
	v_pk_fma_f32 v[110:111], v[110:111], v[172:173], v[126:127]
	s_or_b64 exec, exec, s[10:11]
	v_cvt_pk_bf16_f32 v104, v104, v105
	v_cvt_pk_bf16_f32 v105, v106, v107
	v_cvt_pk_bf16_f32 v106, v108, v109
	v_cvt_pk_bf16_f32 v107, v110, v111
	global_store_dwordx4 v[240:241], v[104:107], off
	v_add_u32_e32 v244, 24, v198
	v_and_b32_e32 v245, 0x1fff, v244
	v_add_u32_e32 v246, 24, v211
	v_and_or_b32 v246, v246, 15, v85
	v_cmp_gt_i32_e32 vcc, s3, v244
	s_nop 1
	v_cndmask_b32_e32 v245, v246, v245, vcc
	v_lshlrev_b32_e32 v246, 7, v245
	v_mov_b32_e32 v247, 0
	v_lshl_add_u64 v[246:247], v[192:193], 0, v[246:247]
	global_load_dwordx4 v[162:165], v[246:247], off offset:64
	global_load_dwordx4 v[166:169], v[246:247], off offset:80
	global_load_dwordx4 v[170:173], v[246:247], off offset:16
	global_load_dwordx4 v[174:177], v[246:247], off
	ds_read_b128 v[112:115], v212 offset:12480
	ds_read_b128 v[116:119], v212 offset:12496
	v_add_u32_e32 v242, 12, v198
	v_mad_i64_i32 v[242:243], s[10:11], v242, s15, v[64:65]
	s_waitcnt vmcnt(15)
	v_fmamk_f32 v238, v223, 0x3b800000, v84
	v_mul_f32_e32 v239, 0x4b800000, v238
	v_cmp_gt_f32_e32 vcc, s5, v238
	s_nop 1
	v_cndmask_b32_e32 v238, v238, v239, vcc
	v_rsq_f32_e32 v238, v238
	s_nop 0
	v_mul_f32_e32 v239, 0x45800000, v238
	v_cndmask_b32_e32 v238, v238, v239, vcc
	s_waitcnt lgkmcnt(0)
	v_pk_mul_f32 v[112:113], v[112:113], v[238:239] op_sel_hi:[1,0]
	v_pk_mul_f32 v[114:115], v[114:115], v[238:239] op_sel_hi:[1,0]
	v_pk_mul_f32 v[116:117], v[116:117], v[238:239] op_sel_hi:[1,0]
	v_pk_mul_f32 v[118:119], v[118:119], v[238:239] op_sel_hi:[1,0]
	s_nop 1
	v_mov_b32_dpp v228, v112 quad_perm:[2,3,0,1] row_mask:0xf bank_mask:0xf bound_ctrl:1
	v_mov_b32_dpp v229, v113 quad_perm:[2,3,0,1] row_mask:0xf bank_mask:0xf bound_ctrl:1
	v_mov_b32_dpp v230, v114 quad_perm:[2,3,0,1] row_mask:0xf bank_mask:0xf bound_ctrl:1
	v_mov_b32_dpp v231, v115 quad_perm:[2,3,0,1] row_mask:0xf bank_mask:0xf bound_ctrl:1
	v_mov_b32_dpp v232, v116 quad_perm:[2,3,0,1] row_mask:0xf bank_mask:0xf bound_ctrl:1
	v_mov_b32_dpp v233, v117 quad_perm:[2,3,0,1] row_mask:0xf bank_mask:0xf bound_ctrl:1
	v_mov_b32_dpp v234, v118 quad_perm:[2,3,0,1] row_mask:0xf bank_mask:0xf bound_ctrl:1
	v_mov_b32_dpp v235, v119 quad_perm:[2,3,0,1] row_mask:0xf bank_mask:0xf bound_ctrl:1
	s_and_saveexec_b64 s[10:11], s[8:9]
	v_pk_mul_f32 v[228:229], v[194:195], v[228:229]
	v_pk_mul_f32 v[230:231], v[194:195], v[230:231]
	v_pk_mul_f32 v[232:233], v[194:195], v[232:233]
	v_pk_mul_f32 v[234:235], v[194:195], v[234:235]
	v_pk_mul_f32 v[228:229], v[228:229], v[88:89]
	v_pk_mul_f32 v[230:231], v[230:231], v[90:91]
	v_pk_mul_f32 v[232:233], v[232:233], v[92:93]
	v_pk_mul_f32 v[234:235], v[234:235], v[94:95]
	v_pk_fma_f32 v[112:113], v[112:113], v[100:101], v[228:229]
	v_pk_fma_f32 v[114:115], v[114:115], v[102:103], v[230:231]
	v_pk_fma_f32 v[116:117], v[116:117], v[96:97], v[232:233]
	v_pk_fma_f32 v[118:119], v[118:119], v[98:99], v[234:235]
	s_or_b64 exec, exec, s[10:11]
	v_cvt_pk_bf16_f32 v112, v112, v113
	v_cvt_pk_bf16_f32 v113, v114, v115
	v_cvt_pk_bf16_f32 v114, v116, v117
	v_cvt_pk_bf16_f32 v115, v118, v119
	global_store_dwordx4 v[242:243], v[112:115], off
	v_add_u32_e32 v244, 28, v198
	v_and_b32_e32 v245, 0x1fff, v244
	v_add_u32_e32 v246, 28, v211
	v_and_or_b32 v246, v246, 15, v85
	v_cmp_gt_i32_e32 vcc, s3, v244
	s_nop 1
	v_cndmask_b32_e32 v245, v246, v245, vcc
	v_lshlrev_b32_e32 v246, 7, v245
	v_mov_b32_e32 v247, 0
	v_lshl_add_u64 v[246:247], v[192:193], 0, v[246:247]
	global_load_dwordx4 v[88:91], v[246:247], off offset:64
	global_load_dwordx4 v[92:95], v[246:247], off offset:80
	global_load_dwordx4 v[96:99], v[246:247], off offset:16
	global_load_dwordx4 v[100:103], v[246:247], off
	ds_read_b128 v[104:107], v212 offset:16640
	ds_read_b128 v[108:111], v212 offset:16656
	v_add_u32_e32 v240, 16, v198
	v_mad_i64_i32 v[240:241], s[10:11], v240, s15, v[64:65]
	s_waitcnt vmcnt(15)
	v_fmamk_f32 v236, v224, 0x3b800000, v84
	v_mul_f32_e32 v237, 0x4b800000, v236
	v_cmp_gt_f32_e32 vcc, s5, v236
	s_nop 1
	v_cndmask_b32_e32 v236, v236, v237, vcc
	v_rsq_f32_e32 v236, v236
	s_nop 0
	v_mul_f32_e32 v237, 0x45800000, v236
	v_cndmask_b32_e32 v236, v236, v237, vcc
	s_waitcnt lgkmcnt(0)
	v_pk_mul_f32 v[104:105], v[104:105], v[236:237] op_sel_hi:[1,0]
	v_pk_mul_f32 v[106:107], v[106:107], v[236:237] op_sel_hi:[1,0]
	v_pk_mul_f32 v[108:109], v[108:109], v[236:237] op_sel_hi:[1,0]
	v_pk_mul_f32 v[110:111], v[110:111], v[236:237] op_sel_hi:[1,0]
	s_nop 1
	v_mov_b32_dpp v120, v104 quad_perm:[2,3,0,1] row_mask:0xf bank_mask:0xf bound_ctrl:1
	v_mov_b32_dpp v121, v105 quad_perm:[2,3,0,1] row_mask:0xf bank_mask:0xf bound_ctrl:1
	v_mov_b32_dpp v122, v106 quad_perm:[2,3,0,1] row_mask:0xf bank_mask:0xf bound_ctrl:1
	v_mov_b32_dpp v123, v107 quad_perm:[2,3,0,1] row_mask:0xf bank_mask:0xf bound_ctrl:1
	v_mov_b32_dpp v124, v108 quad_perm:[2,3,0,1] row_mask:0xf bank_mask:0xf bound_ctrl:1
	v_mov_b32_dpp v125, v109 quad_perm:[2,3,0,1] row_mask:0xf bank_mask:0xf bound_ctrl:1
	v_mov_b32_dpp v126, v110 quad_perm:[2,3,0,1] row_mask:0xf bank_mask:0xf bound_ctrl:1
	v_mov_b32_dpp v127, v111 quad_perm:[2,3,0,1] row_mask:0xf bank_mask:0xf bound_ctrl:1
	s_and_saveexec_b64 s[10:11], s[8:9]
	v_pk_mul_f32 v[120:121], v[194:195], v[120:121]
	v_pk_mul_f32 v[122:123], v[194:195], v[122:123]
	v_pk_mul_f32 v[124:125], v[194:195], v[124:125]
	v_pk_mul_f32 v[126:127], v[194:195], v[126:127]
	v_pk_mul_f32 v[120:121], v[120:121], v[130:131]
	v_pk_mul_f32 v[122:123], v[122:123], v[132:133]
	v_pk_mul_f32 v[124:125], v[124:125], v[134:135]
	v_pk_mul_f32 v[126:127], v[126:127], v[136:137]
	v_pk_fma_f32 v[104:105], v[104:105], v[142:143], v[120:121]
	v_pk_fma_f32 v[106:107], v[106:107], v[144:145], v[122:123]
	v_pk_fma_f32 v[108:109], v[108:109], v[138:139], v[124:125]
	v_pk_fma_f32 v[110:111], v[110:111], v[140:141], v[126:127]
	s_or_b64 exec, exec, s[10:11]
	v_cvt_pk_bf16_f32 v104, v104, v105
	v_cvt_pk_bf16_f32 v105, v106, v107
	v_cvt_pk_bf16_f32 v106, v108, v109
	v_cvt_pk_bf16_f32 v107, v110, v111
	global_store_dwordx4 v[240:241], v[104:107], off
	ds_read_b128 v[112:115], v212 offset:20800
	ds_read_b128 v[116:119], v212 offset:20816
	v_add_u32_e32 v242, 20, v198
	v_mad_i64_i32 v[242:243], s[10:11], v242, s15, v[64:65]
	s_waitcnt vmcnt(11)
	v_fmamk_f32 v238, v225, 0x3b800000, v84
	v_mul_f32_e32 v239, 0x4b800000, v238
	v_cmp_gt_f32_e32 vcc, s5, v238
	s_nop 1
	v_cndmask_b32_e32 v238, v238, v239, vcc
	v_rsq_f32_e32 v238, v238
	s_nop 0
	v_mul_f32_e32 v239, 0x45800000, v238
	v_cndmask_b32_e32 v238, v238, v239, vcc
	s_waitcnt lgkmcnt(0)
	v_pk_mul_f32 v[112:113], v[112:113], v[238:239] op_sel_hi:[1,0]
	v_pk_mul_f32 v[114:115], v[114:115], v[238:239] op_sel_hi:[1,0]
	v_pk_mul_f32 v[116:117], v[116:117], v[238:239] op_sel_hi:[1,0]
	v_pk_mul_f32 v[118:119], v[118:119], v[238:239] op_sel_hi:[1,0]
	s_nop 1
	v_mov_b32_dpp v228, v112 quad_perm:[2,3,0,1] row_mask:0xf bank_mask:0xf bound_ctrl:1
	v_mov_b32_dpp v229, v113 quad_perm:[2,3,0,1] row_mask:0xf bank_mask:0xf bound_ctrl:1
	v_mov_b32_dpp v230, v114 quad_perm:[2,3,0,1] row_mask:0xf bank_mask:0xf bound_ctrl:1
	v_mov_b32_dpp v231, v115 quad_perm:[2,3,0,1] row_mask:0xf bank_mask:0xf bound_ctrl:1
	v_mov_b32_dpp v232, v116 quad_perm:[2,3,0,1] row_mask:0xf bank_mask:0xf bound_ctrl:1
	v_mov_b32_dpp v233, v117 quad_perm:[2,3,0,1] row_mask:0xf bank_mask:0xf bound_ctrl:1
	v_mov_b32_dpp v234, v118 quad_perm:[2,3,0,1] row_mask:0xf bank_mask:0xf bound_ctrl:1
	v_mov_b32_dpp v235, v119 quad_perm:[2,3,0,1] row_mask:0xf bank_mask:0xf bound_ctrl:1
	s_and_saveexec_b64 s[10:11], s[8:9]
	v_pk_mul_f32 v[228:229], v[194:195], v[228:229]
	v_pk_mul_f32 v[230:231], v[194:195], v[230:231]
	v_pk_mul_f32 v[232:233], v[194:195], v[232:233]
	v_pk_mul_f32 v[234:235], v[194:195], v[234:235]
	v_pk_mul_f32 v[228:229], v[228:229], v[146:147]
	v_pk_mul_f32 v[230:231], v[230:231], v[148:149]
	v_pk_mul_f32 v[232:233], v[232:233], v[150:151]
	v_pk_mul_f32 v[234:235], v[234:235], v[152:153]
	v_pk_fma_f32 v[112:113], v[112:113], v[158:159], v[228:229]
	v_pk_fma_f32 v[114:115], v[114:115], v[160:161], v[230:231]
	v_pk_fma_f32 v[116:117], v[116:117], v[154:155], v[232:233]
	v_pk_fma_f32 v[118:119], v[118:119], v[156:157], v[234:235]
	s_or_b64 exec, exec, s[10:11]
	v_cvt_pk_bf16_f32 v112, v112, v113
	v_cvt_pk_bf16_f32 v113, v114, v115
	v_cvt_pk_bf16_f32 v114, v116, v117
	v_cvt_pk_bf16_f32 v115, v118, v119
	global_store_dwordx4 v[242:243], v[112:115], off
	ds_read_b128 v[104:107], v212 offset:24960
	ds_read_b128 v[108:111], v212 offset:24976
	v_add_u32_e32 v240, 24, v198
	v_mad_i64_i32 v[240:241], s[10:11], v240, s15, v[64:65]
	s_waitcnt vmcnt(7)
	v_fmamk_f32 v236, v226, 0x3b800000, v84
	v_mul_f32_e32 v237, 0x4b800000, v236
	v_cmp_gt_f32_e32 vcc, s5, v236
	s_nop 1
	v_cndmask_b32_e32 v236, v236, v237, vcc
	v_rsq_f32_e32 v236, v236
	s_nop 0
	v_mul_f32_e32 v237, 0x45800000, v236
	v_cndmask_b32_e32 v236, v236, v237, vcc
	s_waitcnt lgkmcnt(0)
	v_pk_mul_f32 v[104:105], v[104:105], v[236:237] op_sel_hi:[1,0]
	v_pk_mul_f32 v[106:107], v[106:107], v[236:237] op_sel_hi:[1,0]
	v_pk_mul_f32 v[108:109], v[108:109], v[236:237] op_sel_hi:[1,0]
	v_pk_mul_f32 v[110:111], v[110:111], v[236:237] op_sel_hi:[1,0]
	s_nop 1
	v_mov_b32_dpp v120, v104 quad_perm:[2,3,0,1] row_mask:0xf bank_mask:0xf bound_ctrl:1
	v_mov_b32_dpp v121, v105 quad_perm:[2,3,0,1] row_mask:0xf bank_mask:0xf bound_ctrl:1
	v_mov_b32_dpp v122, v106 quad_perm:[2,3,0,1] row_mask:0xf bank_mask:0xf bound_ctrl:1
	v_mov_b32_dpp v123, v107 quad_perm:[2,3,0,1] row_mask:0xf bank_mask:0xf bound_ctrl:1
	v_mov_b32_dpp v124, v108 quad_perm:[2,3,0,1] row_mask:0xf bank_mask:0xf bound_ctrl:1
	v_mov_b32_dpp v125, v109 quad_perm:[2,3,0,1] row_mask:0xf bank_mask:0xf bound_ctrl:1
	v_mov_b32_dpp v126, v110 quad_perm:[2,3,0,1] row_mask:0xf bank_mask:0xf bound_ctrl:1
	v_mov_b32_dpp v127, v111 quad_perm:[2,3,0,1] row_mask:0xf bank_mask:0xf bound_ctrl:1
	s_and_saveexec_b64 s[10:11], s[8:9]
	v_pk_mul_f32 v[120:121], v[194:195], v[120:121]
	v_pk_mul_f32 v[122:123], v[194:195], v[122:123]
	v_pk_mul_f32 v[124:125], v[194:195], v[124:125]
	v_pk_mul_f32 v[126:127], v[194:195], v[126:127]
	v_pk_mul_f32 v[120:121], v[120:121], v[162:163]
	v_pk_mul_f32 v[122:123], v[122:123], v[164:165]
	v_pk_mul_f32 v[124:125], v[124:125], v[166:167]
	v_pk_mul_f32 v[126:127], v[126:127], v[168:169]
	v_pk_fma_f32 v[104:105], v[104:105], v[174:175], v[120:121]
	v_pk_fma_f32 v[106:107], v[106:107], v[176:177], v[122:123]
	v_pk_fma_f32 v[108:109], v[108:109], v[170:171], v[124:125]
	v_pk_fma_f32 v[110:111], v[110:111], v[172:173], v[126:127]
	s_or_b64 exec, exec, s[10:11]
	v_cvt_pk_bf16_f32 v104, v104, v105
	v_cvt_pk_bf16_f32 v105, v106, v107
	v_cvt_pk_bf16_f32 v106, v108, v109
	v_cvt_pk_bf16_f32 v107, v110, v111
	global_store_dwordx4 v[240:241], v[104:107], off
	ds_read_b128 v[112:115], v212 offset:29120
	ds_read_b128 v[116:119], v212 offset:29136
	v_add_u32_e32 v242, 28, v198
	v_mad_i64_i32 v[242:243], s[10:11], v242, s15, v[64:65]
	s_waitcnt vmcnt(3)
	v_fmamk_f32 v238, v227, 0x3b800000, v84
	v_mul_f32_e32 v239, 0x4b800000, v238
	v_cmp_gt_f32_e32 vcc, s5, v238
	s_nop 1
	v_cndmask_b32_e32 v238, v238, v239, vcc
	v_rsq_f32_e32 v238, v238
	s_nop 0
	v_mul_f32_e32 v239, 0x45800000, v238
	v_cndmask_b32_e32 v238, v238, v239, vcc
	s_waitcnt lgkmcnt(0)
	v_pk_mul_f32 v[112:113], v[112:113], v[238:239] op_sel_hi:[1,0]
	v_pk_mul_f32 v[114:115], v[114:115], v[238:239] op_sel_hi:[1,0]
	v_pk_mul_f32 v[116:117], v[116:117], v[238:239] op_sel_hi:[1,0]
	v_pk_mul_f32 v[118:119], v[118:119], v[238:239] op_sel_hi:[1,0]
	s_nop 1
	v_mov_b32_dpp v228, v112 quad_perm:[2,3,0,1] row_mask:0xf bank_mask:0xf bound_ctrl:1
	v_mov_b32_dpp v229, v113 quad_perm:[2,3,0,1] row_mask:0xf bank_mask:0xf bound_ctrl:1
	v_mov_b32_dpp v230, v114 quad_perm:[2,3,0,1] row_mask:0xf bank_mask:0xf bound_ctrl:1
	v_mov_b32_dpp v231, v115 quad_perm:[2,3,0,1] row_mask:0xf bank_mask:0xf bound_ctrl:1
	v_mov_b32_dpp v232, v116 quad_perm:[2,3,0,1] row_mask:0xf bank_mask:0xf bound_ctrl:1
	v_mov_b32_dpp v233, v117 quad_perm:[2,3,0,1] row_mask:0xf bank_mask:0xf bound_ctrl:1
	v_mov_b32_dpp v234, v118 quad_perm:[2,3,0,1] row_mask:0xf bank_mask:0xf bound_ctrl:1
	v_mov_b32_dpp v235, v119 quad_perm:[2,3,0,1] row_mask:0xf bank_mask:0xf bound_ctrl:1
	s_and_saveexec_b64 s[10:11], s[8:9]
	v_pk_mul_f32 v[228:229], v[194:195], v[228:229]
	v_pk_mul_f32 v[230:231], v[194:195], v[230:231]
	v_pk_mul_f32 v[232:233], v[194:195], v[232:233]
	v_pk_mul_f32 v[234:235], v[194:195], v[234:235]
	v_pk_mul_f32 v[228:229], v[228:229], v[88:89]
	v_pk_mul_f32 v[230:231], v[230:231], v[90:91]
	v_pk_mul_f32 v[232:233], v[232:233], v[92:93]
	v_pk_mul_f32 v[234:235], v[234:235], v[94:95]
	v_pk_fma_f32 v[112:113], v[112:113], v[100:101], v[228:229]
	v_pk_fma_f32 v[114:115], v[114:115], v[102:103], v[230:231]
	v_pk_fma_f32 v[116:117], v[116:117], v[96:97], v[232:233]
	v_pk_fma_f32 v[118:119], v[118:119], v[98:99], v[234:235]
	s_or_b64 exec, exec, s[10:11]
	v_cvt_pk_bf16_f32 v112, v112, v113
	v_cvt_pk_bf16_f32 v113, v114, v115
	v_cvt_pk_bf16_f32 v114, v116, v117
	v_cvt_pk_bf16_f32 v115, v118, v119
	global_store_dwordx4 v[242:243], v[112:115], off
